# adds: mLSTM seq-loop P2 LDS reads hoisted ahead of the MFMA chain (S^T operands + decay table rows), attention K/V staging vmcnt ladder collapsed to one wait
# baseline (speedup 1.0000x reference)
; #define LAS __attribute__((address_space(3)))
; template <int DV, int PAR, bool KW = true, bool KL = true, bool VL = true>
; __device__ __forceinline__ void attn_iter_full(AttnState<DV>& S, int t, LAS unsigned char* lds) {
;     ...
;     u32x4 pw[4]; float mxa = 0.f, mxb = 0.f, mx = 0.f; f32x16 ssum;
;     constexpr int PD = (DV == 64) ? 3 : 2; bf16x8 fr[PD + 1];
;     ...
; #pragma unroll
;     for (int i = 0; i < PD; ++i) fr[i] = AT_FRAG(i);
;     __builtin_amdgcn_sched_barrier(0);
; #pragma unroll
;     for (int i = 0; i < NS; ++i) {
;         if (i + PD < NS) fr[(i + PD) % (PD + 1)] = AT_FRAG(i + PD);
;         if (i == 3) {
;             if (KW) *(LAS u32x4*)(lds + AT_K0 + PAR * AT_KB + S.kl) = S.kreg;
;             LAS unsigned char* W = lds + AT_V0 + (PAR ^ 1) * AT_VB + S.vl; *(LAS u32x4*)W = S.vreg0; if (DV == 128) *(LAS u32x4*)(W + 64 * 144) = S.vreg1; }
;         if (i == 5) { if (KL) S.kreg = *(const u32x4*)(S.kg + (size_t)(t + 3) * 4096);
;             if (VL) { S.vreg0 = *(const u32x4*)(S.vg + (t + 2) * 64); if (DV == 128) S.vreg1 = *(const u32x4*)(S.vg + (size_t)64 * TK + (t + 2) * 64); } }
;         if (i < 8) { if (i & 1) sn1 = MFMA32(fr[i % (PD + 1)], S.qr[i >> 1], sn1); else sn0 = MFMA32(fr[i % (PD + 1)], S.qr[i >> 1], sn0); }
;         else { const int j = i - 8; S.o[j % NDB] = MFMA32(fr[i % (PD + 1)], __builtin_bit_cast(bf16x8, pw[j / NDB]), S.o[j % NDB]); }
; #pragma unroll
;         for (int u = 0; u < NU; ++u) {
;             if (u * NS / NU != i) continue;
;             if (u < 20) {
;                 const int q = u / 5, r = u % 5;
;                 if (r < 4) { const int e = 8 * q + 2 * r;
;                     if (e < 16) { C0[e] = fast_exp2(C0[e]); C0[e + 1] = fast_exp2(C0[e + 1]); }
;                     else { C1[e - 16] = fast_exp2(C1[e - 16]); C1[e - 15] = fast_exp2(C1[e - 15]); } }
;                 else { if (q < 2) { const int b0 = 8 * q; pw[q].x = pk2(C0[b0], C0[b0 + 1]); pw[q].y = pk2(C0[b0 + 2], C0[b0 + 3]); pw[q].z = pk2(C0[b0 + 4], C0[b0 + 5]); pw[q].w = pk2(C0[b0 + 6], C0[b0 + 7]); }
;                        else { const int b0 = 8 * (q - 2); pw[q].x = pk2(C1[b0], C1[b0 + 1]); pw[q].y = pk2(C1[b0 + 2], C1[b0 + 3]); pw[q].z = pk2(C1[b0 + 4], C1[b0 + 5]); pw[q].w = pk2(C1[b0 + 6], C1[b0 + 7]); } }
;             } else if (u == 20) { ssum = C0 + C1; }
.LBB0_397:
	ds_read_b128 v[32:35], v169 offset:9216
	ds_read_b128 v[36:39], v169 offset:13824
	ds_read_b128 v[40:43], v169 offset:9248
	s_waitcnt lgkmcnt(2)
	v_mfma_f32_32x32x16_bf16 v[112:127], v[32:35], v[140:143], v[64:79]
	ds_read_b128 v[44:47], v169 offset:13856
	v_exp_f32_e32 v32, v82
	v_exp_f32_e32 v34, v80
	v_exp_f32_e32 v35, v81
	v_exp_f32_e32 v33, v83
	s_waitcnt lgkmcnt(2)
	v_mfma_f32_32x32x16_bf16 v[96:111], v[36:39], v[140:143], v[64:79]
	ds_read_b128 v[80:83], v169 offset:9280
	v_exp_f32_e32 v38, v84
	v_exp_f32_e32 v39, v85
	v_exp_f32_e32 v36, v86
	v_exp_f32_e32 v37, v87
	s_waitcnt lgkmcnt(2)
	v_mfma_f32_32x32x16_bf16 v[112:127], v[40:43], v[136:139], v[112:127]
	ds_read_b128 v[84:87], v169 offset:13888
	v_lshl_add_u64 v[162:163], v[156:157], 0, v[160:161]
	v_lshl_add_u64 v[164:165], v[158:159], 0, v[160:161]
	v_cvt_pk_bf16_f32 v40, v34, v35
	v_cvt_pk_bf16_f32 v41, v32, v33
	v_cvt_pk_bf16_f32 v42, v38, v39
	v_cvt_pk_bf16_f32 v43, v36, v37
	v_exp_f32_e32 v176, v88
	v_exp_f32_e32 v177, v89
	s_waitcnt lgkmcnt(2)
	v_mfma_f32_32x32x16_bf16 v[96:111], v[44:47], v[136:139], v[96:111]
	ds_read_b128 v[172:175], v169 offset:9312
	s_waitcnt vmcnt(0)
	ds_write_b128 v168, v[144:147]
	ds_write_b128 v168, v[148:151] offset:36864
	v_exp_f32_e32 v178, v90
	v_exp_f32_e32 v179, v91
	s_waitcnt lgkmcnt(4)
	v_mfma_f32_32x32x16_bf16 v[112:127], v[80:83], v[132:135], v[112:127]
	ds_read_b128 v[44:47], v169 offset:13920
	v_exp_f32_e32 v92, v92
	v_exp_f32_e32 v93, v93
	v_exp_f32_e32 v94, v94
	v_exp_f32_e32 v95, v95
	s_mov_b32 s4, 0x16306000
	v_add_co_u32_e32 v88, vcc, s4, v162
	s_mov_b32 s4, 0x16c00000
	s_nop 0
	v_addc_co_u32_e32 v89, vcc, 0, v163, vcc
	v_add_co_u32_e32 v164, vcc, s4, v164
	ds_read_b128 v[80:83], v167 offset:18432
	s_nop 0
	v_addc_co_u32_e32 v165, vcc, 0, v165, vcc
	global_load_dwordx4 v[144:147], v[88:89], off
	global_load_dwordx4 v[148:151], v[164:165], off offset:256
	s_waitcnt lgkmcnt(5)
	v_mfma_f32_32x32x16_bf16 v[96:111], v[84:87], v[132:135], v[96:111]
	v_cvt_pk_bf16_f32 v84, v176, v177
	v_exp_f32_e32 v180, v48
	v_exp_f32_e32 v181, v49
	v_cvt_pk_bf16_f32 v85, v178, v179
	v_cvt_pk_bf16_f32 v86, v92, v93
	v_cvt_pk_bf16_f32 v87, v94, v95
	s_waitcnt lgkmcnt(4)
	v_mfma_f32_32x32x16_bf16 v[112:127], v[172:175], v[128:131], v[112:127]
	ds_read_b128 v[88:91], v167 offset:23040
	v_exp_f32_e32 v172, v50
	v_exp_f32_e32 v173, v51
	s_waitcnt lgkmcnt(2)
	v_mfma_f32_32x32x16_bf16 v[96:111], v[44:47], v[128:131], v[96:111]
	ds_read_b128 v[48:51], v167 offset:18464
	v_exp_f32_e32 v174, v52
	v_exp_f32_e32 v175, v53
	v_exp_f32_e32 v182, v54
	v_exp_f32_e32 v183, v55
	s_waitcnt lgkmcnt(2)
	v_mfma_f32_32x32x16_bf16 v[0:15], v[80:83], v[40:43], v[0:15]
	ds_read_b128 v[44:47], v167 offset:23072
	v_cvt_pk_bf16_f32 v52, v180, v181
	v_cvt_pk_bf16_f32 v53, v172, v173
	v_cvt_pk_bf16_f32 v54, v174, v175
	v_cvt_pk_bf16_f32 v55, v182, v183
	v_exp_f32_e32 v56, v56
	v_exp_f32_e32 v57, v57
	s_waitcnt lgkmcnt(2)
	v_mfma_f32_32x32x16_bf16 v[16:31], v[88:91], v[40:43], v[16:31]
	ds_read_b128 v[80:83], v167 offset:18496
	v_exp_f32_e32 v58, v58
	v_exp_f32_e32 v59, v59
	s_waitcnt lgkmcnt(2)
	v_mfma_f32_32x32x16_bf16 v[0:15], v[48:51], v[84:87], v[0:15]
	ds_read_b128 v[40:43], v167 offset:23104
	v_exp_f32_e32 v60, v60
	v_exp_f32_e32 v61, v61
	v_exp_f32_e32 v62, v62
	v_exp_f32_e32 v63, v63
	s_waitcnt lgkmcnt(2)
	v_mfma_f32_32x32x16_bf16 v[16:31], v[44:47], v[84:87], v[16:31]
	ds_read_b128 v[48:51], v167 offset:18528
	v_cvt_pk_bf16_f32 v44, v56, v57
	v_cvt_pk_bf16_f32 v45, v58, v59
	v_cvt_pk_bf16_f32 v46, v60, v61
	v_cvt_pk_bf16_f32 v47, v62, v63
	v_pk_add_f32 v[60:61], v[60:61], v[92:93]
	v_pk_add_f32 v[62:63], v[62:63], v[94:95]
	v_pk_add_f32 v[58:59], v[58:59], v[178:179]
	v_pk_add_f32 v[56:57], v[56:57], v[176:177]
	v_pk_add_f32 v[38:39], v[174:175], v[38:39]
	v_pk_add_f32 v[84:85], v[180:181], v[34:35]
	v_pk_add_f32 v[36:37], v[182:183], v[36:37]
	v_pk_add_f32 v[86:87], v[172:173], v[32:33]
	s_waitcnt lgkmcnt(2)
	v_mfma_f32_32x32x16_bf16 v[0:15], v[80:83], v[52:55], v[0:15]
	v_add_f32_e64 v36, v86, v36
	v_add_f32_e64 v37, v87, v37
	v_add_f32_e64 v38, v84, v38
	v_add_f32_e64 v39, v85, v39
	v_add_f32_e64 v36, v58, v36
	v_add_f32_e64 v37, v59, v37
	v_pk_add_f32 v[38:39], v[56:57], v[38:39]
	ds_read_b128 v[32:35], v167 offset:23136
	v_pk_add_f32 v[36:37], v[62:63], v[36:37]
	v_pk_add_f32 v[38:39], v[60:61], v[38:39]
	s_nop 0
	v_pk_mov_b32 v[56:57], v[38:39], v[36:37] op_sel:[1,0]
	v_mov_b32_e32 v39, v37
	v_pk_add_f32 v[36:37], v[56:57], v[38:39]
	s_nop 0
	v_add_f32_e32 v36, v36, v37
	v_add_f32_e32 v171, v171, v36
	s_waitcnt lgkmcnt(2)
	v_mfma_f32_32x32x16_bf16 v[16:31], v[40:43], v[52:55], v[16:31]
	v_max3_f32 v36, v112, v113, v96
	v_max3_f32 v37, v114, v115, v97
	v_max3_f32 v36, v36, v98, v99
	v_max3_f32 v37, v37, v118, v119
	v_max3_f32 v36, v36, v116, v117
	v_max3_f32 v37, v37, v102, v103
	v_max3_f32 v36, v36, v100, v101
	s_waitcnt lgkmcnt(1)
	v_mfma_f32_32x32x16_bf16 v[0:15], v[48:51], v[44:47], v[0:15]
	v_max3_f32 v36, v36, v120, v121
	v_max3_f32 v37, v37, v122, v123
	v_max3_f32 v36, v36, v104, v105
	v_max3_f32 v37, v37, v106, v107
	v_max3_f32 v36, v36, v124, v125
	v_max3_f32 v37, v37, v126, v127
	v_max3_f32 v36, v36, v108, v109
	v_max3_f32 v37, v37, v110, v111
	s_waitcnt lgkmcnt(0)
	v_mfma_f32_32x32x16_bf16 v[16:31], v[32:35], v[44:47], v[16:31]
	v_max_f32_e32 v32, v36, v37
	v_mov_b32_e32 v33, v32
	s_nop 1
	v_permlane32_swap_b32_e32 v32, v33
	v_max_f32_e32 v32, v32, v33
	s_nop 0
	v_cmp_lt_f32_e32 vcc, s3, v32
	s_cbranch_vccz .LBB0_399
; #define LAS __attribute__((address_space(3)))
; __device__ __forceinline__ float fast_exp2(float x) { return __builtin_amdgcn_exp2f(x); }
; #define MFMA32(a, b, c) __builtin_amdgcn_mfma_f32_32x32x16_bf16((a), (b), (c), 0, 0, 0)
; template <int DV, int PAR, bool KW = true, bool KL = true, bool VL = true>
; __device__ __forceinline__ void attn_iter_full(AttnState<DV>& S, int t, LAS unsigned char* lds) {
;     ...
;     u32x4 pw[4]; float mxa = 0.f, mxb = 0.f, mx = 0.f; f32x16 ssum;
;     constexpr int PD = (DV == 64) ? 3 : 2; bf16x8 fr[PD + 1];
;     ...
; #pragma unroll
;     for (int i = 0; i < PD; ++i) fr[i] = AT_FRAG(i);
;     __builtin_amdgcn_sched_barrier(0);
; #pragma unroll
;     for (int i = 0; i < NS; ++i) {
;         if (i + PD < NS) fr[(i + PD) % (PD + 1)] = AT_FRAG(i + PD);
;         if (i == 3) {
;             if (KW) *(LAS u32x4*)(lds + AT_K0 + PAR * AT_KB + S.kl) = S.kreg;
;             LAS unsigned char* W = lds + AT_V0 + (PAR ^ 1) * AT_VB + S.vl; *(LAS u32x4*)W = S.vreg0; if (DV == 128) *(LAS u32x4*)(W + 64 * 144) = S.vreg1; }
;         if (i == 5) { if (KL) S.kreg = *(const u32x4*)(S.kg + (size_t)(t + 3) * 4096);
;             if (VL) { S.vreg0 = *(const u32x4*)(S.vg + (t + 2) * 64); if (DV == 128) S.vreg1 = *(const u32x4*)(S.vg + (size_t)64 * TK + (t + 2) * 64); } }
;         if (i < 8) { if (i & 1) sn1 = MFMA32(fr[i % (PD + 1)], S.qr[i >> 1], sn1); else sn0 = MFMA32(fr[i % (PD + 1)], S.qr[i >> 1], sn0); }
;         else { const int j = i - 8; S.o[j % NDB] = MFMA32(fr[i % (PD + 1)], __builtin_bit_cast(bf16x8, pw[j / NDB]), S.o[j % NDB]); }
; #pragma unroll
;         for (int u = 0; u < NU; ++u) {
;             if (u * NS / NU != i) continue;
;             if (u < 20) {
;                 const int q = u / 5, r = u % 5;
;     ...
;     if (__any(mx > 8.0f)) {
;         const float dl = fmaxf(mx, 0.f), alpha = fast_exp2(-dl);
;         S.mrun += dl; S.lsum *= alpha;
; #pragma unroll
;         for (int i = 0; i < 16; ++i) { sn0[i] -= dl; sn1[i] -= dl; S.negm[i] = -S.mrun; }
; #pragma unroll
;         for (int d = 0; d < NDB; ++d)
; #pragma unroll
;             for (int i = 0; i < 16; ++i) S.o[d][i] *= alpha;
;     }
;     __syncthreads();
	v_max_f32_e32 v32, v32, v32
	v_max_f32_e32 v34, 0, v32
	v_exp_f32_e64 v36, -v34
	v_add_f32_e32 v170, v170, v34
	v_xor_b32_e32 v32, 0x80000000, v170
	v_pk_add_f32 v[112:113], v[112:113], v[34:35] op_sel_hi:[1,0] neg_lo:[0,1] neg_hi:[0,1]
	v_mul_f32_e32 v171, v171, v36
	v_pk_add_f32 v[96:97], v[96:97], v[34:35] op_sel_hi:[1,0] neg_lo:[0,1] neg_hi:[0,1]
	v_pk_add_f32 v[114:115], v[114:115], v[34:35] op_sel_hi:[1,0] neg_lo:[0,1] neg_hi:[0,1]
	v_pk_add_f32 v[98:99], v[98:99], v[34:35] op_sel_hi:[1,0] neg_lo:[0,1] neg_hi:[0,1]
	v_pk_add_f32 v[116:117], v[116:117], v[34:35] op_sel_hi:[1,0] neg_lo:[0,1] neg_hi:[0,1]
	v_pk_add_f32 v[100:101], v[100:101], v[34:35] op_sel_hi:[1,0] neg_lo:[0,1] neg_hi:[0,1]
	v_pk_add_f32 v[118:119], v[118:119], v[34:35] op_sel_hi:[1,0] neg_lo:[0,1] neg_hi:[0,1]
	v_pk_add_f32 v[102:103], v[102:103], v[34:35] op_sel_hi:[1,0] neg_lo:[0,1] neg_hi:[0,1]
	v_pk_add_f32 v[120:121], v[120:121], v[34:35] op_sel_hi:[1,0] neg_lo:[0,1] neg_hi:[0,1]
	v_pk_add_f32 v[104:105], v[104:105], v[34:35] op_sel_hi:[1,0] neg_lo:[0,1] neg_hi:[0,1]
	v_pk_add_f32 v[122:123], v[122:123], v[34:35] op_sel_hi:[1,0] neg_lo:[0,1] neg_hi:[0,1]
	v_pk_add_f32 v[106:107], v[106:107], v[34:35] op_sel_hi:[1,0] neg_lo:[0,1] neg_hi:[0,1]
	v_pk_add_f32 v[124:125], v[124:125], v[34:35] op_sel_hi:[1,0] neg_lo:[0,1] neg_hi:[0,1]
	v_pk_add_f32 v[108:109], v[108:109], v[34:35] op_sel_hi:[1,0] neg_lo:[0,1] neg_hi:[0,1]
	v_pk_add_f32 v[126:127], v[126:127], v[34:35] op_sel_hi:[1,0] neg_lo:[0,1] neg_hi:[0,1]
	v_pk_add_f32 v[110:111], v[110:111], v[34:35] op_sel_hi:[1,0] neg_lo:[0,1] neg_hi:[0,1]
	v_pk_mul_f32 v[14:15], v[14:15], v[36:37] op_sel_hi:[1,0]
	v_pk_mul_f32 v[12:13], v[12:13], v[36:37] op_sel_hi:[1,0]
	v_pk_mul_f32 v[10:11], v[10:11], v[36:37] op_sel_hi:[1,0]
	v_pk_mul_f32 v[8:9], v[8:9], v[36:37] op_sel_hi:[1,0]
	v_pk_mul_f32 v[6:7], v[6:7], v[36:37] op_sel_hi:[1,0]
	v_pk_mul_f32 v[4:5], v[4:5], v[36:37] op_sel_hi:[1,0]
	v_pk_mul_f32 v[2:3], v[2:3], v[36:37] op_sel_hi:[1,0]
	v_pk_mul_f32 v[0:1], v[0:1], v[36:37] op_sel_hi:[1,0]
	v_pk_mul_f32 v[30:31], v[30:31], v[36:37] op_sel_hi:[1,0]
	v_pk_mul_f32 v[28:29], v[28:29], v[36:37] op_sel_hi:[1,0]
	v_pk_mul_f32 v[26:27], v[26:27], v[36:37] op_sel_hi:[1,0]
	v_pk_mul_f32 v[24:25], v[24:25], v[36:37] op_sel_hi:[1,0]
	v_pk_mul_f32 v[22:23], v[22:23], v[36:37] op_sel_hi:[1,0]
	v_pk_mul_f32 v[20:21], v[20:21], v[36:37] op_sel_hi:[1,0]
	v_pk_mul_f32 v[18:19], v[18:19], v[36:37] op_sel_hi:[1,0]
	v_pk_mul_f32 v[16:17], v[16:17], v[36:37] op_sel_hi:[1,0]
	v_mov_b32_e32 v33, v32
	v_mov_b32_e32 v34, v32
	v_mov_b32_e32 v35, v32
	v_mov_b32_e32 v36, v32
	v_mov_b32_e32 v37, v32
	v_mov_b32_e32 v38, v32
	v_mov_b32_e32 v39, v32
	v_mov_b32_e32 v40, v32
	v_mov_b32_e32 v41, v32
	v_mov_b32_e32 v42, v32
	v_mov_b32_e32 v43, v32
	v_mov_b32_e32 v44, v32
	v_mov_b32_e32 v45, v32
	v_mov_b32_e32 v46, v32
	v_mov_b32_e32 v47, v32
	v_mov_b32_e32 v64, v32
	v_mov_b32_e32 v65, v32
	v_mov_b32_e32 v66, v32
	v_mov_b32_e32 v67, v32
	v_mov_b32_e32 v68, v32
	v_mov_b32_e32 v69, v32
	v_mov_b32_e32 v70, v32
	v_mov_b32_e32 v71, v32
	v_mov_b32_e32 v72, v32
	v_mov_b32_e32 v73, v32
	v_mov_b32_e32 v74, v32
	v_mov_b32_e32 v75, v32
	v_mov_b32_e32 v76, v32
	v_mov_b32_e32 v77, v32
	v_mov_b32_e32 v78, v32
	v_mov_b32_e32 v79, v32
	s_branch .LBB0_400
.LBB0_399:
.LBB0_400:
	s_barrier
	ds_read_b128 v[48:51], v169
	ds_read_b128 v[172:175], v169 offset:4608
	ds_read_b128 v[176:179], v169 offset:32
	s_waitcnt lgkmcnt(2)
	v_mfma_f32_32x32x16_bf16 v[80:95], v[48:51], v[140:143], v[64:79]
	ds_read_b128 v[180:183], v169 offset:4640
	v_exp_f32_e32 v184, v112
	v_exp_f32_e32 v185, v113
	v_exp_f32_e32 v186, v114
	v_exp_f32_e32 v187, v115
	s_waitcnt lgkmcnt(2)
	v_mfma_f32_32x32x16_bf16 v[48:63], v[172:175], v[140:143], v[64:79]
	ds_read_b128 v[112:115], v169 offset:64
	v_exp_f32_e32 v188, v116
	v_exp_f32_e32 v189, v117
	v_exp_f32_e32 v190, v118
	v_exp_f32_e32 v191, v119
	s_waitcnt lgkmcnt(2)
	v_mfma_f32_32x32x16_bf16 v[80:95], v[176:179], v[136:139], v[80:95]
	ds_read_b128 v[116:119], v169 offset:4672
	v_cvt_pk_bf16_f32 v172, v184, v185
	v_cvt_pk_bf16_f32 v173, v186, v187
	v_cvt_pk_bf16_f32 v174, v188, v189
	v_cvt_pk_bf16_f32 v175, v190, v191
	v_exp_f32_e32 v192, v120
	v_exp_f32_e32 v193, v121
	s_waitcnt lgkmcnt(2)
	v_mfma_f32_32x32x16_bf16 v[48:63], v[180:183], v[136:139], v[48:63]
	ds_read_b128 v[176:179], v169 offset:96
	s_waitcnt vmcnt(0)
	ds_write_b128 v168, v[144:147] offset:9216
	ds_write_b128 v168, v[148:151] offset:18432
	v_exp_f32_e32 v196, v122
	v_exp_f32_e32 v197, v123
	s_waitcnt lgkmcnt(4)
	v_mfma_f32_32x32x16_bf16 v[80:95], v[112:115], v[132:135], v[80:95]
	ds_read_b128 v[120:123], v169 offset:4704
	v_exp_f32_e32 v180, v124
	v_exp_f32_e32 v181, v125
	v_exp_f32_e32 v182, v126
	v_exp_f32_e32 v183, v127
	s_mov_b32 s4, 0x16308000
	v_add_co_u32_e32 v124, vcc, s4, v162
	ds_read_b128 v[112:115], v167 offset:36864
	s_nop 0
	v_addc_co_u32_e32 v125, vcc, 0, v163, vcc
	global_load_dwordx4 v[144:147], v[124:125], off
	global_load_dwordx4 v[148:151], v[164:165], off offset:384
	s_waitcnt lgkmcnt(5)
	v_mfma_f32_32x32x16_bf16 v[48:63], v[116:119], v[132:135], v[48:63]
	v_cvt_pk_bf16_f32 v116, v192, v193
	v_exp_f32_e32 v162, v96
	v_exp_f32_e32 v163, v97
	v_cvt_pk_bf16_f32 v117, v196, v197
	v_cvt_pk_bf16_f32 v118, v180, v181
	v_cvt_pk_bf16_f32 v119, v182, v183
	s_waitcnt lgkmcnt(4)
	v_mfma_f32_32x32x16_bf16 v[80:95], v[176:179], v[128:131], v[80:95]
	ds_read_b128 v[124:127], v167 offset:41472
	v_exp_f32_e32 v164, v98
	v_exp_f32_e32 v165, v99
	s_waitcnt lgkmcnt(2)
; template <int DV, int PAR, bool KW = true, bool KL = true, bool VL = true>
; __device__ __forceinline__ void attn_iter_full(AttnState<DV>& S, int t, LAS unsigned char* lds) {
;     ...
;         if (i < 8) { if (i & 1) sn1 = MFMA32(fr[i % (PD + 1)], S.qr[i >> 1], sn1); else sn0 = MFMA32(fr[i % (PD + 1)], S.qr[i >> 1], sn0); }
;         else { const int j = i - 8; S.o[j % NDB] = MFMA32(fr[i % (PD + 1)], __builtin_bit_cast(bf16x8, pw[j / NDB]), S.o[j % NDB]); }
; #pragma unroll
;         for (int u = 0; u < NU; ++u) {
;             if (u * NS / NU != i) continue;
;             if (u < 20) {
;                 const int q = u / 5, r = u % 5;
;                 if (r < 4) { const int e = 8 * q + 2 * r;
;                     if (e < 16) { C0[e] = fast_exp2(C0[e]); C0[e + 1] = fast_exp2(C0[e + 1]); }
;                     else { C1[e - 16] = fast_exp2(C1[e - 16]); C1[e - 15] = fast_exp2(C1[e - 15]); } }
;                 else { if (q < 2) { const int b0 = 8 * q; pw[q].x = pk2(C0[b0], C0[b0 + 1]); pw[q].y = pk2(C0[b0 + 2], C0[b0 + 3]); pw[q].z = pk2(C0[b0 + 4], C0[b0 + 5]); pw[q].w = pk2(C0[b0 + 6], C0[b0 + 7]); }
;                        else { const int b0 = 8 * (q - 2); pw[q].x = pk2(C1[b0], C1[b0 + 1]); pw[q].y = pk2(C1[b0 + 2], C1[b0 + 3]); pw[q].z = pk2(C1[b0 + 4], C1[b0 + 5]); pw[q].w = pk2(C1[b0 + 6], C1[b0 + 7]); } }
;             } else if (u == 20) { ssum = C0 + C1; }
;             else if (u == 21) { const f32x4 a = (f32x4){ssum[0], ssum[1], ssum[2], ssum[3]} + (f32x4){ssum[4], ssum[5], ssum[6], ssum[7]} + (f32x4){ssum[8], ssum[9], ssum[10], ssum[11]} + (f32x4){ssum[12], ssum[13], ssum[14], ssum[15]};
;                 S.lsum += (a[0] + a[1]) + (a[2] + a[3]); }
;             else if (u == 22) { mxa = max3f(sn0[0], sn0[1], sn1[0]); mxb = max3f(sn0[2], sn0[3], sn1[1]); mxa = max3f(mxa, sn1[2], sn1[3]); }
;             else if (u < 26) { const int r = 4 * (u - 22); mxa = max3f(mxa, sn0[r], sn0[r + 1]); mxb = max3f(mxb, sn0[r + 2], sn0[r + 3]); mxa = max3f(mxa, sn1[r], sn1[r + 1]); mxb = max3f(mxb, sn1[r + 2], sn1[r + 3]); }
;             else { const float m = max2f(mxa, mxb); auto rr = __builtin_amdgcn_permlane32_swap(__float_as_uint(m), __float_as_uint(m), false, false); mx = max2f(__uint_as_float(rr[0]), __uint_as_float(rr[1])); }
;         }
;         __builtin_amdgcn_sched_barrier(0);
;     }
;     ...
;     if (__any(mx > 8.0f)) {
	v_mfma_f32_32x32x16_bf16 v[48:63], v[120:123], v[128:131], v[48:63]
	ds_read_b128 v[96:99], v167 offset:36896
	v_exp_f32_e32 v176, v100
	v_exp_f32_e32 v177, v101
	v_exp_f32_e32 v178, v102
	v_exp_f32_e32 v179, v103
	s_waitcnt lgkmcnt(2)
	v_mfma_f32_32x32x16_bf16 v[0:15], v[112:115], v[172:175], v[0:15]
	ds_read_b128 v[100:103], v167 offset:41504
	v_cvt_pk_bf16_f32 v112, v162, v163
	v_cvt_pk_bf16_f32 v113, v164, v165
	v_cvt_pk_bf16_f32 v114, v176, v177
	v_cvt_pk_bf16_f32 v115, v178, v179
	v_exp_f32_e32 v198, v104
	v_exp_f32_e32 v199, v105
	s_waitcnt lgkmcnt(2)
	v_mfma_f32_32x32x16_bf16 v[16:31], v[124:127], v[172:175], v[16:31]
	ds_read_b128 v[120:123], v167 offset:36928
	v_exp_f32_e32 v124, v106
	v_exp_f32_e32 v125, v107
	s_waitcnt lgkmcnt(2)
	v_mfma_f32_32x32x16_bf16 v[0:15], v[96:99], v[116:119], v[0:15]
	ds_read_b128 v[104:107], v167 offset:41536
	v_exp_f32_e32 v108, v108
	v_exp_f32_e32 v109, v109
	v_exp_f32_e32 v110, v110
	v_exp_f32_e32 v111, v111
	s_waitcnt lgkmcnt(2)
	v_mfma_f32_32x32x16_bf16 v[16:31], v[100:103], v[116:119], v[16:31]
	ds_read_b128 v[96:99], v167 offset:36960
	v_cvt_pk_bf16_f32 v100, v198, v199
	v_cvt_pk_bf16_f32 v101, v124, v125
	v_cvt_pk_bf16_f32 v102, v108, v109
	v_cvt_pk_bf16_f32 v103, v110, v111
	v_pk_add_f32 v[116:117], v[108:109], v[180:181]
	v_pk_add_f32 v[118:119], v[110:111], v[182:183]
	v_pk_add_f32 v[124:125], v[124:125], v[196:197]
	v_pk_add_f32 v[126:127], v[198:199], v[192:193]
	v_pk_add_f32 v[172:173], v[176:177], v[188:189]
	v_pk_add_f32 v[162:163], v[162:163], v[184:185]
	v_pk_add_f32 v[174:175], v[178:179], v[190:191]
	v_pk_add_f32 v[164:165], v[164:165], v[186:187]
	s_waitcnt lgkmcnt(2)
	v_mfma_f32_32x32x16_bf16 v[0:15], v[120:123], v[112:115], v[0:15]
	v_add_f32_e64 v120, v164, v174
	v_add_f32_e64 v121, v165, v175
	v_add_f32_e64 v122, v162, v172
	v_add_f32_e64 v123, v163, v173
	v_add_f32_e64 v120, v124, v120
	v_add_f32_e64 v121, v125, v121
	v_pk_add_f32 v[122:123], v[126:127], v[122:123]
	v_pk_add_f32 v[118:119], v[118:119], v[120:121]
	v_pk_add_f32 v[116:117], v[116:117], v[122:123]
	ds_read_b128 v[108:111], v167 offset:41568
	v_pk_mov_b32 v[120:121], v[116:117], v[118:119] op_sel:[1,0]
	v_mov_b32_e32 v117, v119
	v_pk_add_f32 v[116:117], v[120:121], v[116:117]
	s_nop 0
	v_add_f32_e32 v116, v116, v117
	v_add_f32_e32 v171, v171, v116
	s_waitcnt lgkmcnt(2)
	v_mfma_f32_32x32x16_bf16 v[16:31], v[104:107], v[112:115], v[16:31]
	v_max3_f32 v104, v80, v81, v48
	v_max3_f32 v105, v82, v83, v49
	v_max3_f32 v104, v104, v50, v51
	v_max3_f32 v105, v105, v86, v87
	v_max3_f32 v104, v104, v84, v85
	v_max3_f32 v105, v105, v54, v55
	v_max3_f32 v104, v104, v52, v53
	s_waitcnt lgkmcnt(1)
	v_mfma_f32_32x32x16_bf16 v[0:15], v[96:99], v[100:103], v[0:15]
	v_max3_f32 v96, v104, v88, v89
	v_max3_f32 v97, v105, v90, v91
	v_max3_f32 v96, v96, v56, v57
	v_max3_f32 v97, v97, v58, v59
	v_max3_f32 v96, v96, v92, v93
	v_max3_f32 v97, v97, v94, v95
	v_max3_f32 v96, v96, v60, v61
	v_max3_f32 v97, v97, v62, v63
	s_waitcnt lgkmcnt(0)
	v_mfma_f32_32x32x16_bf16 v[16:31], v[108:111], v[100:103], v[16:31]
	v_max_f32_e32 v96, v96, v97
	v_mov_b32_e32 v97, v96
	s_nop 1
	v_permlane32_swap_b32_e32 v96, v97
	v_max_f32_e32 v96, v96, v97
	s_nop 0
	v_cmp_lt_f32_e32 vcc, s3, v96
	s_cbranch_vccz .LBB0_396
	v_max_f32_e32 v32, v96, v96
	v_max_f32_e32 v33, 0, v32
	v_exp_f32_e64 v34, -v33
	v_add_f32_e32 v170, v170, v33
	v_xor_b32_e32 v32, 0x80000000, v170
	v_sub_f32_e32 v95, v95, v33
	v_mul_f32_e32 v171, v171, v34
	v_sub_f32_e32 v94, v94, v33
	v_sub_f32_e32 v93, v93, v33
	v_sub_f32_e32 v92, v92, v33
	v_sub_f32_e32 v91, v91, v33
	v_sub_f32_e32 v90, v90, v33
	v_sub_f32_e32 v89, v89, v33
	v_sub_f32_e32 v88, v88, v33
	v_sub_f32_e32 v87, v87, v33
	v_sub_f32_e32 v86, v86, v33
	v_sub_f32_e32 v85, v85, v33
	v_sub_f32_e32 v84, v84, v33
	v_sub_f32_e32 v83, v83, v33
	v_sub_f32_e32 v82, v82, v33
	v_sub_f32_e32 v81, v81, v33
	v_sub_f32_e32 v80, v80, v33
	v_sub_f32_e32 v63, v63, v33
	v_sub_f32_e32 v62, v62, v33
	v_sub_f32_e32 v61, v61, v33
	v_sub_f32_e32 v60, v60, v33
	v_sub_f32_e32 v59, v59, v33
	v_sub_f32_e32 v58, v58, v33
	v_sub_f32_e32 v57, v57, v33
	v_sub_f32_e32 v56, v56, v33
	v_sub_f32_e32 v55, v55, v33
	v_sub_f32_e32 v54, v54, v33
	v_sub_f32_e32 v53, v53, v33
	v_sub_f32_e32 v52, v52, v33
	v_sub_f32_e32 v51, v51, v33
	v_sub_f32_e32 v50, v50, v33
	v_sub_f32_e32 v49, v49, v33
	v_sub_f32_e32 v48, v48, v33
	v_pk_mul_f32 v[14:15], v[14:15], v[34:35] op_sel_hi:[1,0]
	v_pk_mul_f32 v[12:13], v[12:13], v[34:35] op_sel_hi:[1,0]
	v_pk_mul_f32 v[10:11], v[10:11], v[34:35] op_sel_hi:[1,0]
	v_pk_mul_f32 v[8:9], v[8:9], v[34:35] op_sel_hi:[1,0]
	v_pk_mul_f32 v[6:7], v[6:7], v[34:35] op_sel_hi:[1,0]
	v_pk_mul_f32 v[4:5], v[4:5], v[34:35] op_sel_hi:[1,0]
	v_pk_mul_f32 v[2:3], v[2:3], v[34:35] op_sel_hi:[1,0]
	v_pk_mul_f32 v[0:1], v[0:1], v[34:35] op_sel_hi:[1,0]
	v_pk_mul_f32 v[30:31], v[30:31], v[34:35] op_sel_hi:[1,0]
	v_pk_mul_f32 v[28:29], v[28:29], v[34:35] op_sel_hi:[1,0]
	v_pk_mul_f32 v[26:27], v[26:27], v[34:35] op_sel_hi:[1,0]
	v_pk_mul_f32 v[24:25], v[24:25], v[34:35] op_sel_hi:[1,0]
	v_pk_mul_f32 v[22:23], v[22:23], v[34:35] op_sel_hi:[1,0]
	v_pk_mul_f32 v[20:21], v[20:21], v[34:35] op_sel_hi:[1,0]
	v_pk_mul_f32 v[18:19], v[18:19], v[34:35] op_sel_hi:[1,0]
	v_pk_mul_f32 v[16:17], v[16:17], v[34:35] op_sel_hi:[1,0]
	v_mov_b32_e32 v33, v32
	v_mov_b32_e32 v34, v32
	v_mov_b32_e32 v35, v32
	v_mov_b32_e32 v36, v32
	v_mov_b32_e32 v37, v32
	v_mov_b32_e32 v38, v32
	v_mov_b32_e32 v39, v32
	v_mov_b32_e32 v40, v32
	v_mov_b32_e32 v41, v32
	v_mov_b32_e32 v42, v32
	v_mov_b32_e32 v43, v32
	v_mov_b32_e32 v44, v32
	v_mov_b32_e32 v45, v32
	v_mov_b32_e32 v46, v32
	v_mov_b32_e32 v47, v32
	v_mov_b32_e32 v64, v32
	v_mov_b32_e32 v65, v32
	v_mov_b32_e32 v66, v32
	v_mov_b32_e32 v67, v32
	v_mov_b32_e32 v68, v32
	v_mov_b32_e32 v69, v32
	v_mov_b32_e32 v70, v32
	v_mov_b32_e32 v71, v32
	v_mov_b32_e32 v72, v32
	v_mov_b32_e32 v73, v32
	v_mov_b32_e32 v74, v32
	v_mov_b32_e32 v75, v32
	v_mov_b32_e32 v76, v32
	v_mov_b32_e32 v77, v32
	v_mov_b32_e32 v78, v32
	v_mov_b32_e32 v79, v32
	s_branch .LBB0_396

; #define LAS __attribute__((address_space(3)))
; template <int DV, int PAR, bool KW = true, bool KL = true, bool VL = true>
; __device__ __forceinline__ void attn_iter_full(AttnState<DV>& S, int t, LAS unsigned char* lds) {
;     ...
;     u32x4 pw[4]; float mxa = 0.f, mxb = 0.f, mx = 0.f; f32x16 ssum;
;     constexpr int PD = (DV == 64) ? 3 : 2; bf16x8 fr[PD + 1];
;     ...
; #pragma unroll
;     for (int i = 0; i < PD; ++i) fr[i] = AT_FRAG(i);
;     __builtin_amdgcn_sched_barrier(0);
; #pragma unroll
;     for (int i = 0; i < NS; ++i) {
;         if (i + PD < NS) fr[(i + PD) % (PD + 1)] = AT_FRAG(i + PD);
;         if (i == 3) {
;             if (KW) *(LAS u32x4*)(lds + AT_K0 + PAR * AT_KB + S.kl) = S.kreg;
;             LAS unsigned char* W = lds + AT_V0 + (PAR ^ 1) * AT_VB + S.vl; *(LAS u32x4*)W = S.vreg0; if (DV == 128) *(LAS u32x4*)(W + 64 * 144) = S.vreg1; }
;         if (i == 5) { if (KL) S.kreg = *(const u32x4*)(S.kg + (size_t)(t + 3) * 4096);
;             if (VL) { S.vreg0 = *(const u32x4*)(S.vg + (t + 2) * 64); if (DV == 128) S.vreg1 = *(const u32x4*)(S.vg + (size_t)64 * TK + (t + 2) * 64); } }
;         if (i < 8) { if (i & 1) sn1 = MFMA32(fr[i % (PD + 1)], S.qr[i >> 1], sn1); else sn0 = MFMA32(fr[i % (PD + 1)], S.qr[i >> 1], sn0); }
;         else { const int j = i - 8; S.o[j % NDB] = MFMA32(fr[i % (PD + 1)], __builtin_bit_cast(bf16x8, pw[j / NDB]), S.o[j % NDB]); }
; #pragma unroll
;         for (int u = 0; u < NU; ++u) {
;             if (u * NS / NU != i) continue;
;             if (u < 20) {
;                 const int q = u / 5, r = u % 5;
;                 if (r < 4) { const int e = 8 * q + 2 * r;
;                     if (e < 16) { C0[e] = fast_exp2(C0[e]); C0[e + 1] = fast_exp2(C0[e + 1]); }
;                     else { C1[e - 16] = fast_exp2(C1[e - 16]); C1[e - 15] = fast_exp2(C1[e - 15]); } }
;                 else { if (q < 2) { const int b0 = 8 * q; pw[q].x = pk2(C0[b0], C0[b0 + 1]); pw[q].y = pk2(C0[b0 + 2], C0[b0 + 3]); pw[q].z = pk2(C0[b0 + 4], C0[b0 + 5]); pw[q].w = pk2(C0[b0 + 6], C0[b0 + 7]); }
;                        else { const int b0 = 8 * (q - 2); pw[q].x = pk2(C1[b0], C1[b0 + 1]); pw[q].y = pk2(C1[b0 + 2], C1[b0 + 3]); pw[q].z = pk2(C1[b0 + 4], C1[b0 + 5]); pw[q].w = pk2(C1[b0 + 6], C1[b0 + 7]); } }
;             } else if (u == 20) { ssum = C0 + C1; }
.LBB0_414:
	ds_read_b128 v[64:67], v231 offset:9216
	ds_read_b128 v[68:71], v231 offset:13824
	s_waitcnt lgkmcnt(1)
	v_mfma_f32_32x32x16_bf16 v[144:159], v[64:67], v[174:177], v[96:111]
	ds_read_b128 v[72:75], v231 offset:9248
	v_exp_f32_e32 v64, v114
	v_exp_f32_e32 v66, v112
	v_exp_f32_e32 v67, v113
	v_exp_f32_e32 v65, v115
	s_waitcnt lgkmcnt(1)
	v_mfma_f32_32x32x16_bf16 v[128:143], v[68:71], v[174:177], v[96:111]
	ds_read_b128 v[76:79], v231 offset:13856
	v_exp_f32_e32 v68, v116
	v_exp_f32_e32 v69, v117
	s_waitcnt lgkmcnt(1)
	v_mfma_f32_32x32x16_bf16 v[144:159], v[72:75], v[170:173], v[144:159]
	ds_read_b128 v[112:115], v231 offset:9280
	v_lshl_add_u64 v[210:211], v[206:207], 0, v[160:161]
	v_lshl_add_u64 v[190:191], v[208:209], 0, v[160:161]
	v_exp_f32_e32 v70, v118
	v_exp_f32_e32 v71, v119
	s_waitcnt lgkmcnt(1)
	v_mfma_f32_32x32x16_bf16 v[128:143], v[76:79], v[170:173], v[128:143]
	ds_read_b128 v[116:119], v231 offset:13888
	s_waitcnt vmcnt(0)
	ds_write_b128 v232, v[178:181]
	ds_write_b128 v232, v[182:185] offset:36864
	ds_write_b128 v232, v[186:189] offset:46080
	v_cvt_pk_bf16_f32 v74, v66, v67
	v_cvt_pk_bf16_f32 v75, v64, v65
	v_cvt_pk_bf16_f32 v76, v68, v69
	v_cvt_pk_bf16_f32 v77, v70, v71
	s_waitcnt lgkmcnt(4)
	v_mfma_f32_32x32x16_bf16 v[144:159], v[112:115], v[166:169], v[144:159]
	ds_read_b128 v[234:237], v231 offset:9312
	v_exp_f32_e32 v72, v120
	v_exp_f32_e32 v73, v121
	s_mov_b32 s15, 0x10e06000
	v_add_co_u32_e32 v78, vcc, s15, v210
	ds_read_b128 v[112:115], v231 offset:13920
	s_nop 0
	v_addc_co_u32_e32 v79, vcc, 0, v211, vcc
	v_add_co_u32_e32 v212, vcc, s16, v190
	global_load_dwordx4 v[178:181], v[78:79], off
	s_nop 0
	v_addc_co_u32_e32 v213, vcc, 0, v191, vcc
	v_add_co_u32_e32 v214, vcc, s17, v190
	global_load_dwordx4 v[182:185], v[212:213], off offset:256
	s_nop 0
	v_addc_co_u32_e32 v215, vcc, 0, v191, vcc
	global_load_dwordx4 v[186:189], v[214:215], off offset:256
	s_waitcnt lgkmcnt(5)
	v_mfma_f32_32x32x16_bf16 v[128:143], v[116:119], v[166:169], v[128:143]
	v_exp_f32_e32 v190, v122
	v_exp_f32_e32 v191, v123
	s_waitcnt lgkmcnt(1)
	v_mfma_f32_32x32x16_bf16 v[144:159], v[234:237], v[162:165], v[144:159]
	ds_read_b128 v[116:119], v230 offset:18432
	v_exp_f32_e32 v124, v124
	v_exp_f32_e32 v125, v125
	s_waitcnt lgkmcnt(1)
	v_mfma_f32_32x32x16_bf16 v[128:143], v[112:115], v[162:165], v[128:143]
	ds_read_b128 v[120:123], v230 offset:23040
	v_exp_f32_e32 v126, v126
	v_exp_f32_e32 v127, v127
	s_waitcnt lgkmcnt(1)
	v_mfma_f32_32x32x16_bf16 v[48:63], v[116:119], v[74:77], v[48:63]
	ds_read_b128 v[112:115], v230 offset:27648
	v_cvt_pk_bf16_f32 v116, v72, v73
	v_cvt_pk_bf16_f32 v117, v190, v191
	v_cvt_pk_bf16_f32 v118, v124, v125
	v_cvt_pk_bf16_f32 v119, v126, v127
	v_exp_f32_e32 v192, v80
	v_exp_f32_e32 v193, v81
	s_waitcnt lgkmcnt(1)
	v_mfma_f32_32x32x16_bf16 v[32:47], v[120:123], v[74:77], v[32:47]
	ds_read_b128 v[78:81], v230 offset:32256
	v_exp_f32_e32 v196, v82
	v_exp_f32_e32 v197, v83
	s_waitcnt lgkmcnt(1)
	v_mfma_f32_32x32x16_bf16 v[16:31], v[112:115], v[74:77], v[16:31]
	ds_read_b128 v[120:123], v230 offset:18464
	v_exp_f32_e32 v198, v84
	v_exp_f32_e32 v199, v85
	s_waitcnt lgkmcnt(1)
	v_mfma_f32_32x32x16_bf16 v[0:15], v[78:81], v[74:77], v[0:15]
	ds_read_b128 v[82:85], v230 offset:23072
	v_exp_f32_e32 v234, v86
	v_exp_f32_e32 v235, v87
	s_waitcnt lgkmcnt(1)
	v_mfma_f32_32x32x16_bf16 v[48:63], v[120:123], v[116:119], v[48:63]
	ds_read_b128 v[74:77], v230 offset:27680
	v_cvt_pk_bf16_f32 v78, v192, v193
	v_cvt_pk_bf16_f32 v79, v196, v197
	v_cvt_pk_bf16_f32 v80, v198, v199
	v_cvt_pk_bf16_f32 v81, v234, v235
	s_waitcnt lgkmcnt(1)
	v_mfma_f32_32x32x16_bf16 v[32:47], v[82:85], v[116:119], v[32:47]
	ds_read_b128 v[112:115], v230 offset:32288
	v_exp_f32_e32 v120, v88
	v_exp_f32_e32 v121, v89
	s_waitcnt lgkmcnt(1)
	v_mfma_f32_32x32x16_bf16 v[16:31], v[74:77], v[116:119], v[16:31]
	ds_read_b128 v[82:85], v230 offset:18496
	v_exp_f32_e32 v122, v90
	v_exp_f32_e32 v123, v91
	s_waitcnt lgkmcnt(1)
	v_mfma_f32_32x32x16_bf16 v[0:15], v[112:115], v[116:119], v[0:15]
	ds_read_b128 v[74:77], v230 offset:23104
	v_exp_f32_e32 v112, v92
	v_exp_f32_e32 v113, v93
	s_waitcnt lgkmcnt(1)
	v_mfma_f32_32x32x16_bf16 v[48:63], v[82:85], v[78:81], v[48:63]
	ds_read_b128 v[86:89], v230 offset:27712
	v_exp_f32_e32 v94, v94
	v_exp_f32_e32 v95, v95
	v_cvt_pk_bf16_f32 v82, v120, v121
	v_cvt_pk_bf16_f32 v83, v122, v123
	v_cvt_pk_bf16_f32 v84, v112, v113
	v_cvt_pk_bf16_f32 v85, v94, v95
	s_waitcnt lgkmcnt(1)
	v_mfma_f32_32x32x16_bf16 v[32:47], v[74:77], v[78:81], v[32:47]
	ds_read_b128 v[90:93], v230 offset:32320
	v_add_f32_e64 v74, v112, v124
	v_add_f32_e64 v75, v113, v125
	v_add_f32_e64 v76, v94, v126
	v_add_f32_e64 v77, v95, v127
	v_pk_add_f32 v[94:95], v[122:123], v[190:191]
	v_pk_add_f32 v[72:73], v[120:121], v[72:73]
	v_pk_add_f32 v[68:69], v[198:199], v[68:69]
	v_pk_add_f32 v[112:113], v[192:193], v[66:67]
	v_pk_add_f32 v[70:71], v[234:235], v[70:71]
	v_pk_add_f32 v[114:115], v[196:197], v[64:65]
	s_waitcnt lgkmcnt(1)
	v_mfma_f32_32x32x16_bf16 v[16:31], v[86:89], v[78:81], v[16:31]
	v_add_f32_e64 v70, v114, v70
	v_add_f32_e64 v71, v115, v71
	v_add_f32_e64 v68, v112, v68
	v_add_f32_e64 v69, v113, v69
	v_add_f32_e64 v70, v94, v70
	v_add_f32_e64 v71, v95, v71
	v_pk_add_f32 v[68:69], v[72:73], v[68:69]
	ds_read_b128 v[64:67], v230 offset:18528
	v_pk_add_f32 v[70:71], v[76:77], v[70:71]
	v_pk_add_f32 v[68:69], v[74:75], v[68:69]
	s_nop 0
	v_pk_mov_b32 v[72:73], v[68:69], v[70:71] op_sel:[1,0]
	v_mov_b32_e32 v69, v71
	v_pk_add_f32 v[68:69], v[72:73], v[68:69]
	s_nop 0
	v_add_f32_e32 v68, v68, v69
	v_add_f32_e32 v234, v216, v68
	s_waitcnt lgkmcnt(1)
	v_mfma_f32_32x32x16_bf16 v[0:15], v[90:93], v[78:81], v[0:15]
	ds_read_b128 v[68:71], v230 offset:23136
	v_max3_f32 v72, v144, v145, v128
	v_max3_f32 v76, v146, v147, v129
	v_max3_f32 v77, v72, v130, v131
	s_waitcnt lgkmcnt(1)
	v_mfma_f32_32x32x16_bf16 v[48:63], v[64:67], v[82:85], v[48:63]
	ds_read_b128 v[72:75], v230 offset:27744
	v_max3_f32 v64, v77, v148, v149
	v_max3_f32 v65, v76, v150, v151
	v_max3_f32 v76, v64, v132, v133
	v_max3_f32 v77, v65, v134, v135
	s_waitcnt lgkmcnt(1)
	v_mfma_f32_32x32x16_bf16 v[32:47], v[68:71], v[82:85], v[32:47]
	ds_read_b128 v[64:67], v230 offset:32352
	v_max3_f32 v68, v76, v152, v153
	v_max3_f32 v69, v77, v154, v155
	v_max3_f32 v68, v68, v136, v137
	v_max3_f32 v69, v69, v138, v139
	s_waitcnt lgkmcnt(1)
	v_mfma_f32_32x32x16_bf16 v[16:31], v[72:75], v[82:85], v[16:31]
	v_max3_f32 v68, v68, v156, v157
	v_max3_f32 v69, v69, v158, v159
	v_max3_f32 v68, v68, v140, v141
	v_max3_f32 v69, v69, v142, v143
	s_waitcnt lgkmcnt(0)
	v_mfma_f32_32x32x16_bf16 v[0:15], v[64:67], v[82:85], v[0:15]
	v_max_f32_e32 v64, v68, v69
	v_mov_b32_e32 v65, v64
	s_nop 1
	v_permlane32_swap_b32_e32 v64, v65
	v_max_f32_e32 v64, v64, v65
	s_nop 0
	v_cmp_lt_f32_e32 vcc, s3, v64
	s_cbranch_vccz .LBB0_416
; __device__ __forceinline__ float fast_exp2(float x) { return __builtin_amdgcn_exp2f(x); }
; template <int DV, int PAR, bool KW = true, bool KL = true, bool VL = true>
; __device__ __forceinline__ void attn_iter_full(AttnState<DV>& S, int t, LAS unsigned char* lds) {
;     ...
;     if (__any(mx > 8.0f)) {
;         const float dl = fmaxf(mx, 0.f), alpha = fast_exp2(-dl);
;         S.mrun += dl; S.lsum *= alpha;
; #pragma unroll
;         for (int i = 0; i < 16; ++i) { sn0[i] -= dl; sn1[i] -= dl; S.negm[i] = -S.mrun; }
; #pragma unroll
;         for (int d = 0; d < NDB; ++d)
; #pragma unroll
;             for (int i = 0; i < 16; ++i) S.o[d][i] *= alpha;
;     }
	v_max_f32_e32 v64, v64, v64
	v_max_f32_e32 v66, 0, v64
	v_exp_f32_e64 v68, -v66
	v_add_f32_e32 v233, v233, v66
	v_xor_b32_e32 v64, 0x80000000, v233
	v_pk_add_f32 v[144:145], v[144:145], v[66:67] op_sel_hi:[1,0] neg_lo:[0,1] neg_hi:[0,1]
	v_mul_f32_e32 v234, v234, v68
	v_pk_add_f32 v[128:129], v[128:129], v[66:67] op_sel_hi:[1,0] neg_lo:[0,1] neg_hi:[0,1]
	v_pk_add_f32 v[146:147], v[146:147], v[66:67] op_sel_hi:[1,0] neg_lo:[0,1] neg_hi:[0,1]
	v_pk_add_f32 v[130:131], v[130:131], v[66:67] op_sel_hi:[1,0] neg_lo:[0,1] neg_hi:[0,1]
	v_pk_add_f32 v[148:149], v[148:149], v[66:67] op_sel_hi:[1,0] neg_lo:[0,1] neg_hi:[0,1]
	v_pk_add_f32 v[132:133], v[132:133], v[66:67] op_sel_hi:[1,0] neg_lo:[0,1] neg_hi:[0,1]
	v_pk_add_f32 v[150:151], v[150:151], v[66:67] op_sel_hi:[1,0] neg_lo:[0,1] neg_hi:[0,1]
	v_pk_add_f32 v[134:135], v[134:135], v[66:67] op_sel_hi:[1,0] neg_lo:[0,1] neg_hi:[0,1]
	v_pk_add_f32 v[152:153], v[152:153], v[66:67] op_sel_hi:[1,0] neg_lo:[0,1] neg_hi:[0,1]
	v_pk_add_f32 v[136:137], v[136:137], v[66:67] op_sel_hi:[1,0] neg_lo:[0,1] neg_hi:[0,1]
	v_pk_add_f32 v[154:155], v[154:155], v[66:67] op_sel_hi:[1,0] neg_lo:[0,1] neg_hi:[0,1]
	v_pk_add_f32 v[138:139], v[138:139], v[66:67] op_sel_hi:[1,0] neg_lo:[0,1] neg_hi:[0,1]
	v_pk_add_f32 v[156:157], v[156:157], v[66:67] op_sel_hi:[1,0] neg_lo:[0,1] neg_hi:[0,1]
	v_pk_add_f32 v[140:141], v[140:141], v[66:67] op_sel_hi:[1,0] neg_lo:[0,1] neg_hi:[0,1]
	v_pk_add_f32 v[158:159], v[158:159], v[66:67] op_sel_hi:[1,0] neg_lo:[0,1] neg_hi:[0,1]
	v_pk_add_f32 v[142:143], v[142:143], v[66:67] op_sel_hi:[1,0] neg_lo:[0,1] neg_hi:[0,1]
	v_pk_mul_f32 v[62:63], v[62:63], v[68:69] op_sel_hi:[1,0]
	v_pk_mul_f32 v[60:61], v[60:61], v[68:69] op_sel_hi:[1,0]
	v_pk_mul_f32 v[58:59], v[58:59], v[68:69] op_sel_hi:[1,0]
	v_pk_mul_f32 v[56:57], v[56:57], v[68:69] op_sel_hi:[1,0]
	v_pk_mul_f32 v[54:55], v[54:55], v[68:69] op_sel_hi:[1,0]
	v_pk_mul_f32 v[52:53], v[52:53], v[68:69] op_sel_hi:[1,0]
	v_pk_mul_f32 v[50:51], v[50:51], v[68:69] op_sel_hi:[1,0]
	v_pk_mul_f32 v[48:49], v[48:49], v[68:69] op_sel_hi:[1,0]
	v_pk_mul_f32 v[46:47], v[46:47], v[68:69] op_sel_hi:[1,0]
	v_pk_mul_f32 v[44:45], v[44:45], v[68:69] op_sel_hi:[1,0]
	v_pk_mul_f32 v[42:43], v[42:43], v[68:69] op_sel_hi:[1,0]
	v_pk_mul_f32 v[40:41], v[40:41], v[68:69] op_sel_hi:[1,0]
	v_pk_mul_f32 v[38:39], v[38:39], v[68:69] op_sel_hi:[1,0]
	v_pk_mul_f32 v[36:37], v[36:37], v[68:69] op_sel_hi:[1,0]
	v_pk_mul_f32 v[34:35], v[34:35], v[68:69] op_sel_hi:[1,0]
	v_pk_mul_f32 v[32:33], v[32:33], v[68:69] op_sel_hi:[1,0]
	v_pk_mul_f32 v[30:31], v[30:31], v[68:69] op_sel_hi:[1,0]
	v_pk_mul_f32 v[28:29], v[28:29], v[68:69] op_sel_hi:[1,0]
	v_pk_mul_f32 v[26:27], v[26:27], v[68:69] op_sel_hi:[1,0]
	v_pk_mul_f32 v[24:25], v[24:25], v[68:69] op_sel_hi:[1,0]
	v_pk_mul_f32 v[22:23], v[22:23], v[68:69] op_sel_hi:[1,0]
	v_pk_mul_f32 v[20:21], v[20:21], v[68:69] op_sel_hi:[1,0]
	v_pk_mul_f32 v[18:19], v[18:19], v[68:69] op_sel_hi:[1,0]
	v_pk_mul_f32 v[16:17], v[16:17], v[68:69] op_sel_hi:[1,0]
	v_pk_mul_f32 v[14:15], v[14:15], v[68:69] op_sel_hi:[1,0]
	v_pk_mul_f32 v[12:13], v[12:13], v[68:69] op_sel_hi:[1,0]
	v_pk_mul_f32 v[10:11], v[10:11], v[68:69] op_sel_hi:[1,0]
	v_pk_mul_f32 v[8:9], v[8:9], v[68:69] op_sel_hi:[1,0]
	v_pk_mul_f32 v[6:7], v[6:7], v[68:69] op_sel_hi:[1,0]
	v_pk_mul_f32 v[4:5], v[4:5], v[68:69] op_sel_hi:[1,0]
	v_pk_mul_f32 v[2:3], v[2:3], v[68:69] op_sel_hi:[1,0]
	v_pk_mul_f32 v[0:1], v[0:1], v[68:69] op_sel_hi:[1,0]
	v_mov_b32_e32 v65, v64
	v_mov_b32_e32 v66, v64
	v_mov_b32_e32 v67, v64
	v_mov_b32_e32 v68, v64
	v_mov_b32_e32 v69, v64
	v_mov_b32_e32 v70, v64
	v_mov_b32_e32 v71, v64
	v_mov_b32_e32 v72, v64
	v_mov_b32_e32 v73, v64
	v_mov_b32_e32 v74, v64
	v_mov_b32_e32 v75, v64
	v_mov_b32_e32 v76, v64
	v_mov_b32_e32 v77, v64
	v_mov_b32_e32 v78, v64
	v_mov_b32_e32 v79, v64
	v_mov_b32_e32 v96, v64
	v_mov_b32_e32 v97, v64
	v_mov_b32_e32 v98, v64
	v_mov_b32_e32 v99, v64
	v_mov_b32_e32 v100, v64
	v_mov_b32_e32 v101, v64
	v_mov_b32_e32 v102, v64
	v_mov_b32_e32 v103, v64
	v_mov_b32_e32 v104, v64
	v_mov_b32_e32 v105, v64
	v_mov_b32_e32 v106, v64
	v_mov_b32_e32 v107, v64
	v_mov_b32_e32 v108, v64
	v_mov_b32_e32 v109, v64
	v_mov_b32_e32 v110, v64
	v_mov_b32_e32 v111, v64
	s_branch .LBB0_417
; #define LAS __attribute__((address_space(3)))
; template <int DV, int PAR, bool KW = true, bool KL = true, bool VL = true>
; __device__ __forceinline__ void attn_iter_full(AttnState<DV>& S, int t, LAS unsigned char* lds) {
;     ...
;     u32x4 pw[4]; float mxa = 0.f, mxb = 0.f, mx = 0.f; f32x16 ssum;
;     constexpr int PD = (DV == 64) ? 3 : 2; bf16x8 fr[PD + 1];
;     ...
; #pragma unroll
;     for (int i = 0; i < PD; ++i) fr[i] = AT_FRAG(i);
;     __builtin_amdgcn_sched_barrier(0);
; #pragma unroll
;     for (int i = 0; i < NS; ++i) {
;         if (i + PD < NS) fr[(i + PD) % (PD + 1)] = AT_FRAG(i + PD);
;         if (i == 3) {
;             if (KW) *(LAS u32x4*)(lds + AT_K0 + PAR * AT_KB + S.kl) = S.kreg;
;             LAS unsigned char* W = lds + AT_V0 + (PAR ^ 1) * AT_VB + S.vl; *(LAS u32x4*)W = S.vreg0; if (DV == 128) *(LAS u32x4*)(W + 64 * 144) = S.vreg1; }
;         if (i == 5) { if (KL) S.kreg = *(const u32x4*)(S.kg + (size_t)(t + 3) * 4096);
;             if (VL) { S.vreg0 = *(const u32x4*)(S.vg + (t + 2) * 64); if (DV == 128) S.vreg1 = *(const u32x4*)(S.vg + (size_t)64 * TK + (t + 2) * 64); } }
;         if (i < 8) { if (i & 1) sn1 = MFMA32(fr[i % (PD + 1)], S.qr[i >> 1], sn1); else sn0 = MFMA32(fr[i % (PD + 1)], S.qr[i >> 1], sn0); }
;         else { const int j = i - 8; S.o[j % NDB] = MFMA32(fr[i % (PD + 1)], __builtin_bit_cast(bf16x8, pw[j / NDB]), S.o[j % NDB]); }
; #pragma unroll
;         for (int u = 0; u < NU; ++u) {
;             if (u * NS / NU != i) continue;
;             if (u < 20) {
;                 const int q = u / 5, r = u % 5;
;                 if (r < 4) { const int e = 8 * q + 2 * r;
;                     if (e < 16) { C0[e] = fast_exp2(C0[e]); C0[e + 1] = fast_exp2(C0[e + 1]); }
;                     else { C1[e - 16] = fast_exp2(C1[e - 16]); C1[e - 15] = fast_exp2(C1[e - 15]); } }
;                 else { if (q < 2) { const int b0 = 8 * q; pw[q].x = pk2(C0[b0], C0[b0 + 1]); pw[q].y = pk2(C0[b0 + 2], C0[b0 + 3]); pw[q].z = pk2(C0[b0 + 4], C0[b0 + 5]); pw[q].w = pk2(C0[b0 + 6], C0[b0 + 7]); }
;                        else { const int b0 = 8 * (q - 2); pw[q].x = pk2(C1[b0], C1[b0 + 1]); pw[q].y = pk2(C1[b0 + 2], C1[b0 + 3]); pw[q].z = pk2(C1[b0 + 4], C1[b0 + 5]); pw[q].w = pk2(C1[b0 + 6], C1[b0 + 7]); } }
;             } else if (u == 20) { ssum = C0 + C1; }
.LBB0_416:
.LBB0_417:
	s_barrier
	ds_read_b128 v[80:83], v231
	ds_read_b128 v[242:245], v231 offset:4608
	s_waitcnt lgkmcnt(1)
	v_mfma_f32_32x32x16_bf16 v[112:127], v[80:83], v[174:177], v[96:111]
	ds_read_b128 v[246:249], v231 offset:32
	v_exp_f32_e32 v216, v144
	v_exp_f32_e32 v217, v145
	v_exp_f32_e32 v144, v146
	v_exp_f32_e32 v145, v147
	s_waitcnt lgkmcnt(1)
	v_mfma_f32_32x32x16_bf16 v[80:95], v[242:245], v[174:177], v[96:111]
	ds_read_b128 v[190:193], v231 offset:4640
	v_exp_f32_e32 v146, v148
	v_exp_f32_e32 v147, v149
	s_waitcnt lgkmcnt(1)
	v_mfma_f32_32x32x16_bf16 v[112:127], v[246:249], v[170:173], v[112:127]
	ds_read_b128 v[242:245], v231 offset:64
	v_exp_f32_e32 v148, v150
	v_exp_f32_e32 v149, v151
	s_waitcnt lgkmcnt(1)
	v_mfma_f32_32x32x16_bf16 v[80:95], v[190:193], v[170:173], v[80:95]
	ds_read_b128 v[246:249], v231 offset:4672
	s_waitcnt vmcnt(0)
	ds_write_b128 v232, v[178:181] offset:9216
	ds_write_b128 v232, v[182:185] offset:18432
	ds_write_b128 v232, v[186:189] offset:27648
	v_cvt_pk_bf16_f32 v196, v216, v217
	v_cvt_pk_bf16_f32 v197, v144, v145
	v_cvt_pk_bf16_f32 v198, v146, v147
	v_cvt_pk_bf16_f32 v199, v148, v149
	s_waitcnt lgkmcnt(4)
	v_mfma_f32_32x32x16_bf16 v[112:127], v[242:245], v[166:169], v[112:127]
	ds_read_b128 v[190:193], v231 offset:96
	v_exp_f32_e32 v150, v152
	v_exp_f32_e32 v151, v153
	s_mov_b32 s15, 0x10e08000
	v_add_co_u32_e32 v152, vcc, s15, v210
	ds_read_b128 v[242:245], v231 offset:4704
	s_nop 0
	v_addc_co_u32_e32 v153, vcc, 0, v211, vcc
	global_load_dwordx4 v[178:181], v[152:153], off
	global_load_dwordx4 v[182:185], v[212:213], off offset:384
	global_load_dwordx4 v[186:189], v[214:215], off offset:384
	s_waitcnt lgkmcnt(5)
	v_mfma_f32_32x32x16_bf16 v[80:95], v[246:249], v[166:169], v[80:95]
	v_exp_f32_e32 v214, v154
	v_exp_f32_e32 v215, v155
	s_waitcnt lgkmcnt(1)
	v_mfma_f32_32x32x16_bf16 v[112:127], v[190:193], v[162:165], v[112:127]
	ds_read_b128 v[152:155], v230 offset:36864
	v_exp_f32_e32 v236, v156
	v_exp_f32_e32 v237, v157
	s_waitcnt lgkmcnt(1)
	v_mfma_f32_32x32x16_bf16 v[80:95], v[242:245], v[162:165], v[80:95]
	ds_read_b128 v[190:193], v230 offset:41472
	v_exp_f32_e32 v242, v158
	v_exp_f32_e32 v243, v159
	s_waitcnt lgkmcnt(1)
	v_mfma_f32_32x32x16_bf16 v[48:63], v[152:155], v[196:199], v[48:63]
	ds_read_b128 v[156:159], v230 offset:46080
	v_cvt_pk_bf16_f32 v152, v150, v151
	v_cvt_pk_bf16_f32 v153, v214, v215
	v_cvt_pk_bf16_f32 v154, v236, v237
	v_cvt_pk_bf16_f32 v155, v242, v243
	v_exp_f32_e32 v244, v128
	v_exp_f32_e32 v245, v129
	s_waitcnt lgkmcnt(1)
	v_mfma_f32_32x32x16_bf16 v[32:47], v[190:193], v[196:199], v[32:47]
	ds_read_b128 v[210:213], v230 offset:50688
	v_exp_f32_e32 v246, v130
	v_exp_f32_e32 v247, v131
	s_waitcnt lgkmcnt(1)
	v_mfma_f32_32x32x16_bf16 v[16:31], v[156:159], v[196:199], v[16:31]
	ds_read_b128 v[128:131], v230 offset:36896
	v_exp_f32_e32 v248, v132
	v_exp_f32_e32 v249, v133
	s_waitcnt lgkmcnt(1)
	v_mfma_f32_32x32x16_bf16 v[0:15], v[210:213], v[196:199], v[0:15]
	ds_read_b128 v[156:159], v230 offset:41504
	v_exp_f32_e32 v196, v134
	v_exp_f32_e32 v197, v135
	s_waitcnt lgkmcnt(1)
	v_mfma_f32_32x32x16_bf16 v[48:63], v[128:131], v[152:155], v[48:63]
	ds_read_b128 v[132:135], v230 offset:46112
	v_cvt_pk_bf16_f32 v128, v244, v245
	v_cvt_pk_bf16_f32 v129, v246, v247
	v_cvt_pk_bf16_f32 v130, v248, v249
	v_cvt_pk_bf16_f32 v131, v196, v197
	s_waitcnt lgkmcnt(1)
	v_mfma_f32_32x32x16_bf16 v[32:47], v[156:159], v[152:155], v[32:47]
	ds_read_b128 v[190:193], v230 offset:50720
	v_exp_f32_e32 v198, v136
	v_exp_f32_e32 v199, v137
	s_waitcnt lgkmcnt(1)
	v_mfma_f32_32x32x16_bf16 v[16:31], v[132:135], v[152:155], v[16:31]
	ds_read_b128 v[156:159], v230 offset:36928
	v_exp_f32_e32 v210, v138
	v_exp_f32_e32 v211, v139
	s_waitcnt lgkmcnt(1)
	v_mfma_f32_32x32x16_bf16 v[0:15], v[190:193], v[152:155], v[0:15]
	ds_read_b128 v[132:135], v230 offset:41536
	v_exp_f32_e32 v190, v140
	v_exp_f32_e32 v191, v141
	s_waitcnt lgkmcnt(1)
	v_mfma_f32_32x32x16_bf16 v[48:63], v[156:159], v[128:131], v[48:63]
	ds_read_b128 v[136:139], v230 offset:46144
	v_exp_f32_e32 v156, v142
	v_exp_f32_e32 v157, v143
	v_cvt_pk_bf16_f32 v140, v198, v199
	v_cvt_pk_bf16_f32 v141, v210, v211
	v_cvt_pk_bf16_f32 v142, v190, v191
	v_cvt_pk_bf16_f32 v143, v156, v157
	s_waitcnt lgkmcnt(1)
	v_mfma_f32_32x32x16_bf16 v[32:47], v[132:135], v[128:131], v[32:47]
	ds_read_b128 v[152:155], v230 offset:50752
	v_add_f32_e64 v158, v190, v236
	v_add_f32_e64 v159, v191, v237
	v_add_f32_e64 v156, v156, v242
	v_add_f32_e64 v157, v157, v243
	v_pk_add_f32 v[190:191], v[210:211], v[214:215]
	v_pk_add_f32 v[150:151], v[198:199], v[150:151]
	v_pk_add_f32 v[146:147], v[248:249], v[146:147]
	v_pk_add_f32 v[192:193], v[244:245], v[216:217]
	v_pk_add_f32 v[148:149], v[196:197], v[148:149]
	v_pk_add_f32 v[144:145], v[246:247], v[144:145]
	s_waitcnt lgkmcnt(1)
	v_mfma_f32_32x32x16_bf16 v[16:31], v[136:139], v[128:131], v[16:31]
	v_add_f32_e64 v136, v144, v148
	v_add_f32_e64 v137, v145, v149
	v_add_f32_e64 v138, v192, v146
	v_add_f32_e64 v139, v193, v147
	v_add_f32_e64 v136, v190, v136
	v_add_f32_e64 v137, v191, v137
	v_pk_add_f32 v[138:139], v[150:151], v[138:139]
	v_pk_add_f32 v[136:137], v[156:157], v[136:137]
	v_pk_add_f32 v[138:139], v[158:159], v[138:139]
	ds_read_b128 v[132:135], v230 offset:36960
	v_pk_mov_b32 v[144:145], v[138:139], v[136:137] op_sel:[1,0]
	v_mov_b32_e32 v139, v137
	v_pk_add_f32 v[136:137], v[144:145], v[138:139]
	s_nop 0
	v_add_f32_e32 v136, v136, v137
	v_add_f32_e32 v216, v234, v136
	s_waitcnt lgkmcnt(1)
	v_mfma_f32_32x32x16_bf16 v[0:15], v[152:155], v[128:131], v[0:15]
	ds_read_b128 v[136:139], v230 offset:41568
	v_max3_f32 v128, v112, v113, v80
	v_max3_f32 v144, v114, v115, v81
	v_max3_f32 v145, v128, v82, v83
	s_waitcnt lgkmcnt(1)
	v_mfma_f32_32x32x16_bf16 v[48:63], v[132:135], v[140:143], v[48:63]
	ds_read_b128 v[128:131], v230 offset:46176
	v_max3_f32 v132, v145, v116, v117
	v_max3_f32 v133, v144, v118, v119
	v_max3_f32 v144, v132, v84, v85
	v_max3_f32 v145, v133, v86, v87
	s_waitcnt lgkmcnt(1)
	v_mfma_f32_32x32x16_bf16 v[32:47], v[136:139], v[140:143], v[32:47]
	ds_read_b128 v[132:135], v230 offset:50784
	v_max3_f32 v136, v144, v120, v121
	v_max3_f32 v137, v145, v122, v123
	v_max3_f32 v136, v136, v88, v89
	v_max3_f32 v137, v137, v90, v91
	s_waitcnt lgkmcnt(1)
	v_mfma_f32_32x32x16_bf16 v[16:31], v[128:131], v[140:143], v[16:31]
	v_max3_f32 v128, v136, v124, v125
	v_max3_f32 v129, v137, v126, v127
	v_max3_f32 v128, v128, v92, v93
	v_max3_f32 v129, v129, v94, v95
	s_waitcnt lgkmcnt(0)
	v_mfma_f32_32x32x16_bf16 v[0:15], v[132:135], v[140:143], v[0:15]
	v_max_f32_e32 v128, v128, v129
	v_mov_b32_e32 v129, v128
	s_nop 1
	v_permlane32_swap_b32_e32 v128, v129
	v_max_f32_e32 v128, v128, v129
	s_nop 0
	v_cmp_lt_f32_e32 vcc, s3, v128
	s_cbranch_vccz .LBB0_413
; __device__ __forceinline__ float fast_exp2(float x) { return __builtin_amdgcn_exp2f(x); }
; template <int DV, int PAR, bool KW = true, bool KL = true, bool VL = true>
; __device__ __forceinline__ void attn_iter_full(AttnState<DV>& S, int t, LAS unsigned char* lds) {
;     ...
;     if (__any(mx > 8.0f)) {
;         const float dl = fmaxf(mx, 0.f), alpha = fast_exp2(-dl);
;         S.mrun += dl; S.lsum *= alpha;
; #pragma unroll
;         for (int i = 0; i < 16; ++i) { sn0[i] -= dl; sn1[i] -= dl; S.negm[i] = -S.mrun; }
; #pragma unroll
;         for (int d = 0; d < NDB; ++d)
; #pragma unroll
;             for (int i = 0; i < 16; ++i) S.o[d][i] *= alpha;
;     }
	v_max_f32_e32 v64, v128, v128
	v_max_f32_e32 v65, 0, v64
	v_exp_f32_e64 v66, -v65
	v_add_f32_e32 v233, v233, v65
	v_xor_b32_e32 v64, 0x80000000, v233
	v_sub_f32_e32 v127, v127, v65
	v_mul_f32_e32 v216, v216, v66
	v_sub_f32_e32 v126, v126, v65
	v_sub_f32_e32 v125, v125, v65
	v_sub_f32_e32 v124, v124, v65
	v_sub_f32_e32 v123, v123, v65
	v_sub_f32_e32 v122, v122, v65
	v_sub_f32_e32 v121, v121, v65
	v_sub_f32_e32 v120, v120, v65
	v_sub_f32_e32 v119, v119, v65
	v_sub_f32_e32 v118, v118, v65
	v_sub_f32_e32 v117, v117, v65
	v_sub_f32_e32 v116, v116, v65
	v_sub_f32_e32 v115, v115, v65
	v_sub_f32_e32 v114, v114, v65
	v_sub_f32_e32 v113, v113, v65
	v_sub_f32_e32 v112, v112, v65
	v_sub_f32_e32 v95, v95, v65
	v_sub_f32_e32 v94, v94, v65
	v_sub_f32_e32 v93, v93, v65
	v_sub_f32_e32 v92, v92, v65
	v_sub_f32_e32 v91, v91, v65
	v_sub_f32_e32 v90, v90, v65
	v_sub_f32_e32 v89, v89, v65
	v_sub_f32_e32 v88, v88, v65
	v_sub_f32_e32 v87, v87, v65
	v_sub_f32_e32 v86, v86, v65
	v_sub_f32_e32 v85, v85, v65
	v_sub_f32_e32 v84, v84, v65
	v_sub_f32_e32 v83, v83, v65
	v_sub_f32_e32 v82, v82, v65
	v_sub_f32_e32 v81, v81, v65
	v_sub_f32_e32 v80, v80, v65
	v_pk_mul_f32 v[62:63], v[62:63], v[66:67] op_sel_hi:[1,0]
	v_pk_mul_f32 v[60:61], v[60:61], v[66:67] op_sel_hi:[1,0]
	v_pk_mul_f32 v[58:59], v[58:59], v[66:67] op_sel_hi:[1,0]
	v_pk_mul_f32 v[56:57], v[56:57], v[66:67] op_sel_hi:[1,0]
	v_pk_mul_f32 v[54:55], v[54:55], v[66:67] op_sel_hi:[1,0]
	v_pk_mul_f32 v[52:53], v[52:53], v[66:67] op_sel_hi:[1,0]
	v_pk_mul_f32 v[50:51], v[50:51], v[66:67] op_sel_hi:[1,0]
	v_pk_mul_f32 v[48:49], v[48:49], v[66:67] op_sel_hi:[1,0]
	v_pk_mul_f32 v[46:47], v[46:47], v[66:67] op_sel_hi:[1,0]
	v_pk_mul_f32 v[44:45], v[44:45], v[66:67] op_sel_hi:[1,0]
	v_pk_mul_f32 v[42:43], v[42:43], v[66:67] op_sel_hi:[1,0]
	v_pk_mul_f32 v[40:41], v[40:41], v[66:67] op_sel_hi:[1,0]
	v_pk_mul_f32 v[38:39], v[38:39], v[66:67] op_sel_hi:[1,0]
	v_pk_mul_f32 v[36:37], v[36:37], v[66:67] op_sel_hi:[1,0]
	v_pk_mul_f32 v[34:35], v[34:35], v[66:67] op_sel_hi:[1,0]
	v_pk_mul_f32 v[32:33], v[32:33], v[66:67] op_sel_hi:[1,0]
	v_pk_mul_f32 v[30:31], v[30:31], v[66:67] op_sel_hi:[1,0]
	v_pk_mul_f32 v[28:29], v[28:29], v[66:67] op_sel_hi:[1,0]
	v_pk_mul_f32 v[26:27], v[26:27], v[66:67] op_sel_hi:[1,0]
	v_pk_mul_f32 v[24:25], v[24:25], v[66:67] op_sel_hi:[1,0]
	v_pk_mul_f32 v[22:23], v[22:23], v[66:67] op_sel_hi:[1,0]
	v_pk_mul_f32 v[20:21], v[20:21], v[66:67] op_sel_hi:[1,0]
	v_pk_mul_f32 v[18:19], v[18:19], v[66:67] op_sel_hi:[1,0]
	v_pk_mul_f32 v[16:17], v[16:17], v[66:67] op_sel_hi:[1,0]
	v_pk_mul_f32 v[14:15], v[14:15], v[66:67] op_sel_hi:[1,0]
	v_pk_mul_f32 v[12:13], v[12:13], v[66:67] op_sel_hi:[1,0]
	v_pk_mul_f32 v[10:11], v[10:11], v[66:67] op_sel_hi:[1,0]
	v_pk_mul_f32 v[8:9], v[8:9], v[66:67] op_sel_hi:[1,0]
	v_pk_mul_f32 v[6:7], v[6:7], v[66:67] op_sel_hi:[1,0]
	v_pk_mul_f32 v[4:5], v[4:5], v[66:67] op_sel_hi:[1,0]
	v_pk_mul_f32 v[2:3], v[2:3], v[66:67] op_sel_hi:[1,0]
	v_pk_mul_f32 v[0:1], v[0:1], v[66:67] op_sel_hi:[1,0]
	v_mov_b32_e32 v65, v64
	v_mov_b32_e32 v66, v64
	v_mov_b32_e32 v67, v64
	v_mov_b32_e32 v68, v64
	v_mov_b32_e32 v69, v64
	v_mov_b32_e32 v70, v64
	v_mov_b32_e32 v71, v64
	v_mov_b32_e32 v72, v64
	v_mov_b32_e32 v73, v64
	v_mov_b32_e32 v74, v64
	v_mov_b32_e32 v75, v64
	v_mov_b32_e32 v76, v64
	v_mov_b32_e32 v77, v64
	v_mov_b32_e32 v78, v64
	v_mov_b32_e32 v79, v64
	v_mov_b32_e32 v96, v64
	v_mov_b32_e32 v97, v64
	v_mov_b32_e32 v98, v64
	v_mov_b32_e32 v99, v64
	v_mov_b32_e32 v100, v64
	v_mov_b32_e32 v101, v64
	v_mov_b32_e32 v102, v64
	v_mov_b32_e32 v103, v64
	v_mov_b32_e32 v104, v64
	v_mov_b32_e32 v105, v64
	v_mov_b32_e32 v106, v64
	v_mov_b32_e32 v107, v64
	v_mov_b32_e32 v108, v64
	v_mov_b32_e32 v109, v64
	v_mov_b32_e32 v110, v64
	v_mov_b32_e32 v111, v64
	s_branch .LBB0_413

; #define LAS __attribute__((address_space(3)))
; template <int DV, int PAR, bool KW = true, bool KL = true, bool VL = true>
; __device__ __forceinline__ void attn_iter_full(AttnState<DV>& S, int t, LAS unsigned char* lds) {
;     ...
;     u32x4 pw[4]; float mxa = 0.f, mxb = 0.f, mx = 0.f; f32x16 ssum;
;     constexpr int PD = (DV == 64) ? 3 : 2; bf16x8 fr[PD + 1];
;     ...
; #pragma unroll
;     for (int i = 0; i < PD; ++i) fr[i] = AT_FRAG(i);
;     __builtin_amdgcn_sched_barrier(0);
; #pragma unroll
;     for (int i = 0; i < NS; ++i) {
;         if (i + PD < NS) fr[(i + PD) % (PD + 1)] = AT_FRAG(i + PD);
;         if (i == 3) {
;             if (KW) *(LAS u32x4*)(lds + AT_K0 + PAR * AT_KB + S.kl) = S.kreg;
;             LAS unsigned char* W = lds + AT_V0 + (PAR ^ 1) * AT_VB + S.vl; *(LAS u32x4*)W = S.vreg0; if (DV == 128) *(LAS u32x4*)(W + 64 * 144) = S.vreg1; }
;         if (i == 5) { if (KL) S.kreg = *(const u32x4*)(S.kg + (size_t)(t + 3) * 4096);
;             if (VL) { S.vreg0 = *(const u32x4*)(S.vg + (t + 2) * 64); if (DV == 128) S.vreg1 = *(const u32x4*)(S.vg + (size_t)64 * TK + (t + 2) * 64); } }
;         if (i < 8) { if (i & 1) sn1 = MFMA32(fr[i % (PD + 1)], S.qr[i >> 1], sn1); else sn0 = MFMA32(fr[i % (PD + 1)], S.qr[i >> 1], sn0); }
;         else { const int j = i - 8; S.o[j % NDB] = MFMA32(fr[i % (PD + 1)], __builtin_bit_cast(bf16x8, pw[j / NDB]), S.o[j % NDB]); }
; #pragma unroll
;         for (int u = 0; u < NU; ++u) {
;             if (u * NS / NU != i) continue;
;             if (u < 20) {
;                 const int q = u / 5, r = u % 5;
;                 if (r < 4) { const int e = 8 * q + 2 * r;
;                     if (e < 16) { C0[e] = fast_exp2(C0[e]); C0[e + 1] = fast_exp2(C0[e + 1]); }
;                     else { C1[e - 16] = fast_exp2(C1[e - 16]); C1[e - 15] = fast_exp2(C1[e - 15]); } }
;                 else { if (q < 2) { const int b0 = 8 * q; pw[q].x = pk2(C0[b0], C0[b0 + 1]); pw[q].y = pk2(C0[b0 + 2], C0[b0 + 3]); pw[q].z = pk2(C0[b0 + 4], C0[b0 + 5]); pw[q].w = pk2(C0[b0 + 6], C0[b0 + 7]); }
;                        else { const int b0 = 8 * (q - 2); pw[q].x = pk2(C1[b0], C1[b0 + 1]); pw[q].y = pk2(C1[b0 + 2], C1[b0 + 3]); pw[q].z = pk2(C1[b0 + 4], C1[b0 + 5]); pw[q].w = pk2(C1[b0 + 6], C1[b0 + 7]); } }
;             } else if (u == 20) { ssum = C0 + C1; }
.LBB0_429:
.LBB0_430:
	s_barrier
	ds_read_b128 v[80:83], v234
	ds_read_b128 v[190:193], v234 offset:4608
	s_waitcnt lgkmcnt(1)
	v_mfma_f32_32x32x16_bf16 v[112:127], v[80:83], v[174:177], v[96:111]
	ds_read_b128 v[196:199], v234 offset:32
	v_exp_f32_e32 v216, v144
	v_exp_f32_e32 v217, v145
	v_exp_f32_e32 v144, v146
	v_exp_f32_e32 v145, v147
	s_waitcnt lgkmcnt(1)
	v_mfma_f32_32x32x16_bf16 v[80:95], v[190:193], v[174:177], v[96:111]
	ds_read_b128 v[242:245], v234 offset:4640
	v_exp_f32_e32 v146, v148
	v_exp_f32_e32 v147, v149
	s_waitcnt lgkmcnt(1)
	v_mfma_f32_32x32x16_bf16 v[112:127], v[196:199], v[170:173], v[112:127]
	ds_read_b128 v[190:193], v234 offset:64
	v_exp_f32_e32 v148, v150
	v_exp_f32_e32 v149, v151
	s_waitcnt lgkmcnt(1)
	v_mfma_f32_32x32x16_bf16 v[80:95], v[242:245], v[170:173], v[80:95]
	ds_read_b128 v[196:199], v234 offset:4672
	s_waitcnt vmcnt(0)
	ds_write_b128 v235, v[178:181] offset:9216
	ds_write_b128 v235, v[182:185] offset:18432
	ds_write_b128 v235, v[186:189] offset:27648
	v_cvt_pk_bf16_f32 v246, v216, v217
	v_cvt_pk_bf16_f32 v247, v144, v145
	v_cvt_pk_bf16_f32 v248, v146, v147
	v_cvt_pk_bf16_f32 v249, v148, v149
	s_waitcnt lgkmcnt(4)
	v_mfma_f32_32x32x16_bf16 v[112:127], v[190:193], v[166:169], v[112:127]
	ds_read_b128 v[242:245], v234 offset:96
	v_exp_f32_e32 v150, v152
	v_exp_f32_e32 v151, v153
	s_mov_b32 s2, 0x10e90000
	v_add_co_u32_e32 v152, vcc, s2, v210
	ds_read_b128 v[190:193], v234 offset:4704
	s_nop 0
	v_addc_co_u32_e32 v153, vcc, 0, v211, vcc
	global_load_dwordx4 v[186:189], v[152:153], off
	global_load_dwordx4 v[178:181], v[212:213], off offset:384
	global_load_dwordx4 v[182:185], v[214:215], off offset:384
	s_waitcnt lgkmcnt(5)
	v_mfma_f32_32x32x16_bf16 v[80:95], v[196:199], v[166:169], v[80:95]
	v_exp_f32_e32 v210, v154
	v_exp_f32_e32 v211, v155
	s_waitcnt lgkmcnt(1)
	v_mfma_f32_32x32x16_bf16 v[112:127], v[242:245], v[162:165], v[112:127]
	ds_read_b128 v[152:155], v233 offset:36864
	v_exp_f32_e32 v212, v156
	v_exp_f32_e32 v213, v157
	s_waitcnt lgkmcnt(1)
	v_mfma_f32_32x32x16_bf16 v[80:95], v[190:193], v[162:165], v[80:95]
	ds_read_b128 v[196:199], v233 offset:41472
	v_exp_f32_e32 v214, v158
	v_exp_f32_e32 v215, v159
	s_waitcnt lgkmcnt(1)
	v_mfma_f32_32x32x16_bf16 v[0:15], v[152:155], v[246:249], v[0:15]
	ds_read_b128 v[156:159], v233 offset:46080
	v_cvt_pk_bf16_f32 v152, v150, v151
	v_cvt_pk_bf16_f32 v153, v210, v211
	v_cvt_pk_bf16_f32 v154, v212, v213
	v_cvt_pk_bf16_f32 v155, v214, v215
	v_exp_f32_e32 v242, v128
	v_exp_f32_e32 v243, v129
	s_waitcnt lgkmcnt(1)
	v_mfma_f32_32x32x16_bf16 v[48:63], v[196:199], v[246:249], v[48:63]
	ds_read_b128 v[190:193], v233 offset:50688
	v_exp_f32_e32 v196, v130
	v_exp_f32_e32 v197, v131
	s_waitcnt lgkmcnt(1)
	v_mfma_f32_32x32x16_bf16 v[32:47], v[156:159], v[246:249], v[32:47]
	ds_read_b128 v[128:131], v233 offset:36896
	v_exp_f32_e32 v198, v132
	v_exp_f32_e32 v199, v133
	s_waitcnt lgkmcnt(1)
	v_mfma_f32_32x32x16_bf16 v[16:31], v[190:193], v[246:249], v[16:31]
	ds_read_b128 v[156:159], v233 offset:41504
	v_exp_f32_e32 v244, v134
	v_exp_f32_e32 v245, v135
	s_waitcnt lgkmcnt(1)
	v_mfma_f32_32x32x16_bf16 v[0:15], v[128:131], v[152:155], v[0:15]
	ds_read_b128 v[132:135], v233 offset:46112
	v_cvt_pk_bf16_f32 v128, v242, v243
	v_cvt_pk_bf16_f32 v129, v196, v197
	v_cvt_pk_bf16_f32 v130, v198, v199
	v_cvt_pk_bf16_f32 v131, v244, v245
	s_waitcnt lgkmcnt(1)
	v_mfma_f32_32x32x16_bf16 v[48:63], v[156:159], v[152:155], v[48:63]
	ds_read_b128 v[190:193], v233 offset:50720
	v_exp_f32_e32 v246, v136
	v_exp_f32_e32 v247, v137
	s_waitcnt lgkmcnt(1)
	v_mfma_f32_32x32x16_bf16 v[32:47], v[132:135], v[152:155], v[32:47]
	ds_read_b128 v[156:159], v233 offset:36928
	v_exp_f32_e32 v248, v138
	v_exp_f32_e32 v249, v139
	s_waitcnt lgkmcnt(1)
	v_mfma_f32_32x32x16_bf16 v[16:31], v[190:193], v[152:155], v[16:31]
	ds_read_b128 v[132:135], v233 offset:41536
	v_exp_f32_e32 v190, v140
	v_exp_f32_e32 v191, v141
	s_waitcnt lgkmcnt(1)
	v_mfma_f32_32x32x16_bf16 v[0:15], v[156:159], v[128:131], v[0:15]
	ds_read_b128 v[136:139], v233 offset:46144
	v_exp_f32_e32 v156, v142
	v_exp_f32_e32 v157, v143
	v_cvt_pk_bf16_f32 v140, v246, v247
	v_cvt_pk_bf16_f32 v141, v248, v249
	v_cvt_pk_bf16_f32 v142, v190, v191
	v_cvt_pk_bf16_f32 v143, v156, v157
	s_waitcnt lgkmcnt(1)
	v_mfma_f32_32x32x16_bf16 v[48:63], v[132:135], v[128:131], v[48:63]
	ds_read_b128 v[152:155], v233 offset:50752
	v_add_f32_e64 v158, v212, v190
	v_add_f32_e64 v159, v213, v191
	v_add_f32_e64 v156, v214, v156
	v_add_f32_e64 v157, v215, v157
	v_pk_add_f32 v[190:191], v[210:211], v[248:249]
	v_pk_add_f32 v[150:151], v[150:151], v[246:247]
	v_pk_add_f32 v[146:147], v[146:147], v[198:199]
	v_pk_add_f32 v[192:193], v[216:217], v[242:243]
	v_pk_add_f32 v[148:149], v[148:149], v[244:245]
	v_pk_add_f32 v[144:145], v[144:145], v[196:197]
	s_waitcnt lgkmcnt(1)
	v_mfma_f32_32x32x16_bf16 v[32:47], v[136:139], v[128:131], v[32:47]
	v_add_f32_e64 v136, v144, v148
	v_add_f32_e64 v137, v145, v149
	v_add_f32_e64 v138, v192, v146
	v_add_f32_e64 v139, v193, v147
	v_add_f32_e64 v136, v190, v136
	v_add_f32_e64 v137, v191, v137
	v_pk_add_f32 v[138:139], v[150:151], v[138:139]
	v_pk_add_f32 v[136:137], v[156:157], v[136:137]
	v_pk_add_f32 v[138:139], v[158:159], v[138:139]
	ds_read_b128 v[132:135], v233 offset:36960
	v_pk_mov_b32 v[144:145], v[138:139], v[136:137] op_sel:[1,0]
	v_mov_b32_e32 v139, v137
	v_pk_add_f32 v[136:137], v[144:145], v[138:139]
	s_nop 0
	v_add_f32_e32 v136, v136, v137
	v_add_f32_e32 v216, v237, v136
	s_waitcnt lgkmcnt(1)
	v_mfma_f32_32x32x16_bf16 v[16:31], v[152:155], v[128:131], v[16:31]
	ds_read_b128 v[136:139], v233 offset:41568
	v_max3_f32 v128, v112, v113, v80
	v_max3_f32 v144, v114, v115, v81
	v_max3_f32 v145, v128, v82, v83
	s_waitcnt lgkmcnt(1)
	v_mfma_f32_32x32x16_bf16 v[0:15], v[132:135], v[140:143], v[0:15]
	ds_read_b128 v[128:131], v233 offset:46176
	v_max3_f32 v132, v145, v116, v117
	v_max3_f32 v133, v144, v118, v119
	v_max3_f32 v144, v132, v84, v85
	v_max3_f32 v145, v133, v86, v87
	s_waitcnt lgkmcnt(1)
	v_mfma_f32_32x32x16_bf16 v[48:63], v[136:139], v[140:143], v[48:63]
	ds_read_b128 v[132:135], v233 offset:50784
	v_max3_f32 v136, v144, v120, v121
	v_max3_f32 v137, v145, v122, v123
	v_max3_f32 v136, v136, v88, v89
	v_max3_f32 v137, v137, v90, v91
	s_waitcnt lgkmcnt(1)
	v_mfma_f32_32x32x16_bf16 v[32:47], v[128:131], v[140:143], v[32:47]
	v_max3_f32 v128, v136, v124, v125
	v_max3_f32 v129, v137, v126, v127
	v_max3_f32 v128, v128, v92, v93
	v_max3_f32 v129, v129, v94, v95
	s_waitcnt lgkmcnt(0)
	v_mfma_f32_32x32x16_bf16 v[16:31], v[132:135], v[140:143], v[16:31]
	v_max_f32_e32 v128, v128, v129
	v_mov_b32_e32 v129, v128
	s_nop 1
	v_permlane32_swap_b32_e32 v128, v129
	v_max_f32_e32 v128, v128, v129
	s_nop 0
	v_cmp_lt_f32_e32 vcc, s3, v128
	s_cbranch_vccz .LBB0_426
; __device__ __forceinline__ float fast_exp2(float x) { return __builtin_amdgcn_exp2f(x); }
; template <int DV, int PAR, bool KW = true, bool KL = true, bool VL = true>
; __device__ __forceinline__ void attn_iter_full(AttnState<DV>& S, int t, LAS unsigned char* lds) {
;     ...
;     if (__any(mx > 8.0f)) {
;         const float dl = fmaxf(mx, 0.f), alpha = fast_exp2(-dl);
;         S.mrun += dl; S.lsum *= alpha;
; #pragma unroll
;         for (int i = 0; i < 16; ++i) { sn0[i] -= dl; sn1[i] -= dl; S.negm[i] = -S.mrun; }
; #pragma unroll
;         for (int d = 0; d < NDB; ++d)
; #pragma unroll
;             for (int i = 0; i < 16; ++i) S.o[d][i] *= alpha;
;     }
	v_max_f32_e32 v64, v128, v128
	v_max_f32_e32 v65, 0, v64
	v_exp_f32_e64 v66, -v65
	v_add_f32_e32 v236, v236, v65
	v_xor_b32_e32 v64, 0x80000000, v236
	v_sub_f32_e32 v127, v127, v65
	v_mul_f32_e32 v216, v216, v66
	v_sub_f32_e32 v126, v126, v65
	v_sub_f32_e32 v125, v125, v65
	v_sub_f32_e32 v124, v124, v65
	v_sub_f32_e32 v123, v123, v65
	v_sub_f32_e32 v122, v122, v65
	v_sub_f32_e32 v121, v121, v65
	v_sub_f32_e32 v120, v120, v65
	v_sub_f32_e32 v119, v119, v65
	v_sub_f32_e32 v118, v118, v65
	v_sub_f32_e32 v117, v117, v65
	v_sub_f32_e32 v116, v116, v65
	v_sub_f32_e32 v115, v115, v65
	v_sub_f32_e32 v114, v114, v65
	v_sub_f32_e32 v113, v113, v65
	v_sub_f32_e32 v112, v112, v65
	v_sub_f32_e32 v95, v95, v65
	v_sub_f32_e32 v94, v94, v65
	v_sub_f32_e32 v93, v93, v65
	v_sub_f32_e32 v92, v92, v65
	v_sub_f32_e32 v91, v91, v65
	v_sub_f32_e32 v90, v90, v65
	v_sub_f32_e32 v89, v89, v65
	v_sub_f32_e32 v88, v88, v65
	v_sub_f32_e32 v87, v87, v65
	v_sub_f32_e32 v86, v86, v65
	v_sub_f32_e32 v85, v85, v65
	v_sub_f32_e32 v84, v84, v65
	v_sub_f32_e32 v83, v83, v65
	v_sub_f32_e32 v82, v82, v65
	v_sub_f32_e32 v81, v81, v65
	v_sub_f32_e32 v80, v80, v65
	v_pk_mul_f32 v[14:15], v[14:15], v[66:67] op_sel_hi:[1,0]
	v_pk_mul_f32 v[12:13], v[12:13], v[66:67] op_sel_hi:[1,0]
	v_pk_mul_f32 v[10:11], v[10:11], v[66:67] op_sel_hi:[1,0]
	v_pk_mul_f32 v[8:9], v[8:9], v[66:67] op_sel_hi:[1,0]
	v_pk_mul_f32 v[6:7], v[6:7], v[66:67] op_sel_hi:[1,0]
	v_pk_mul_f32 v[4:5], v[4:5], v[66:67] op_sel_hi:[1,0]
	v_pk_mul_f32 v[2:3], v[2:3], v[66:67] op_sel_hi:[1,0]
	v_pk_mul_f32 v[0:1], v[0:1], v[66:67] op_sel_hi:[1,0]
	v_pk_mul_f32 v[62:63], v[62:63], v[66:67] op_sel_hi:[1,0]
	v_pk_mul_f32 v[60:61], v[60:61], v[66:67] op_sel_hi:[1,0]
	v_pk_mul_f32 v[58:59], v[58:59], v[66:67] op_sel_hi:[1,0]
	v_pk_mul_f32 v[56:57], v[56:57], v[66:67] op_sel_hi:[1,0]
	v_pk_mul_f32 v[54:55], v[54:55], v[66:67] op_sel_hi:[1,0]
	v_pk_mul_f32 v[52:53], v[52:53], v[66:67] op_sel_hi:[1,0]
	v_pk_mul_f32 v[50:51], v[50:51], v[66:67] op_sel_hi:[1,0]
	v_pk_mul_f32 v[48:49], v[48:49], v[66:67] op_sel_hi:[1,0]
	v_pk_mul_f32 v[46:47], v[46:47], v[66:67] op_sel_hi:[1,0]
	v_pk_mul_f32 v[44:45], v[44:45], v[66:67] op_sel_hi:[1,0]
	v_pk_mul_f32 v[42:43], v[42:43], v[66:67] op_sel_hi:[1,0]
	v_pk_mul_f32 v[40:41], v[40:41], v[66:67] op_sel_hi:[1,0]
	v_pk_mul_f32 v[38:39], v[38:39], v[66:67] op_sel_hi:[1,0]
	v_pk_mul_f32 v[36:37], v[36:37], v[66:67] op_sel_hi:[1,0]
	v_pk_mul_f32 v[34:35], v[34:35], v[66:67] op_sel_hi:[1,0]
	v_pk_mul_f32 v[32:33], v[32:33], v[66:67] op_sel_hi:[1,0]
	v_pk_mul_f32 v[30:31], v[30:31], v[66:67] op_sel_hi:[1,0]
	v_pk_mul_f32 v[28:29], v[28:29], v[66:67] op_sel_hi:[1,0]
	v_pk_mul_f32 v[26:27], v[26:27], v[66:67] op_sel_hi:[1,0]
	v_pk_mul_f32 v[24:25], v[24:25], v[66:67] op_sel_hi:[1,0]
	v_pk_mul_f32 v[22:23], v[22:23], v[66:67] op_sel_hi:[1,0]
	v_pk_mul_f32 v[20:21], v[20:21], v[66:67] op_sel_hi:[1,0]
	v_pk_mul_f32 v[18:19], v[18:19], v[66:67] op_sel_hi:[1,0]
	v_pk_mul_f32 v[16:17], v[16:17], v[66:67] op_sel_hi:[1,0]
	v_mov_b32_e32 v65, v64
	v_mov_b32_e32 v66, v64
	v_mov_b32_e32 v67, v64
	v_mov_b32_e32 v68, v64
	v_mov_b32_e32 v69, v64
	v_mov_b32_e32 v70, v64
	v_mov_b32_e32 v71, v64
	v_mov_b32_e32 v72, v64
	v_mov_b32_e32 v73, v64
	v_mov_b32_e32 v74, v64
	v_mov_b32_e32 v75, v64
	v_mov_b32_e32 v76, v64
	v_mov_b32_e32 v77, v64
	v_mov_b32_e32 v78, v64
	v_mov_b32_e32 v79, v64
	v_mov_b32_e32 v96, v64
	v_mov_b32_e32 v97, v64
	v_mov_b32_e32 v98, v64
	v_mov_b32_e32 v99, v64
	v_mov_b32_e32 v100, v64
	v_mov_b32_e32 v101, v64
	v_mov_b32_e32 v102, v64
	v_mov_b32_e32 v103, v64
	v_mov_b32_e32 v104, v64
	v_mov_b32_e32 v105, v64
	v_mov_b32_e32 v106, v64
	v_mov_b32_e32 v107, v64
	v_mov_b32_e32 v108, v64
	v_mov_b32_e32 v109, v64
	v_mov_b32_e32 v110, v64
	v_mov_b32_e32 v111, v64
	s_branch .LBB0_426

; #define LAS __attribute__((address_space(3)))
; __device__ __forceinline__ unsigned pk2(float lo, float hi) { f32x2_t v = {lo, hi}; bf16x2_t b = __builtin_convertvector(v, bf16x2_t); return __builtin_bit_cast(unsigned, b); }
; __device__ __forceinline__ float fast_exp(float x) { return __builtin_amdgcn_exp2f(x * 1.4426950408889634f); }
; #define MFMA32(a, b, c) __builtin_amdgcn_mfma_f32_32x32x16_bf16((a), (b), (c), 0, 0, 0)
; __device__ __forceinline__ void mlstm_unit(const Params& p, int l, int b, int h, LAS unsigned char* lds) {
;     ...
;             for (int c = 0; c < 4; ++c) { const bf16x8 af = lds_rd16(L + ML_KS + (32 * sblk + r32) * 144 + hi * 16 + c * 32), bfr = lds_rd16(L + ML_QS + (32 * tblk + r32) * 144 + hi * 16 + c * 32); st = MFMA32(af, bfr, st); }
;             const int t = 32 * tblk + r32; const float At = tb[T_BIGA / 4 + t];
;             float dsum = 0.f;
; #pragma unroll
;             for (int ig = 0; ig < 4; ++ig) { const int s0 = 32 * sblk + 8 * ig + 4 * hi; const f32x4 a4 = *(const LAS f32x4*)(L + ML_TAB + T_A + s0 * 4);
;                 float w[4];
; #pragma unroll
;                 for (int e = 0; e < 4; ++e) { const int s = s0 + e; const bool valid = g ? (s >= t) : (s <= t); const float ex = fast_exp(fminf(a4[e] - At, 0.f)); w[e] = valid ? st[4 * ig + e] * ex : 0.f; dsum += w[e]; }
;                 u32x2 pw; pw.x = pk2(w[0], w[1]); pw.y = pk2(w[2], w[3]); *(LAS u32x2*)(L + ML_SW + t * 144 + s0 * 2) = pw; }
;             dsum += __shfl_xor(dsum, 32);
;             if (hi == 0) *(LAS float*)(L + ML_TAB + (sblk ? T_DP1 : T_DP0) + t * 4) = dsum;
.LBB0_464:
	s_waitcnt lgkmcnt(0)
	s_barrier
	ds_read_b128 v[16:19], v135 offset:9216
	ds_read_b128 v[34:37], v135 offset:9248
	ds_read_b128 v[20:23], v116
	ds_read_b128 v[38:41], v116 offset:32
	ds_read_b128 v[162:165], v135 offset:9280
	ds_read_b128 v[166:169], v116 offset:64
	ds_read_b128 v[170:173], v135 offset:9312
	ds_read_b128 v[174:177], v116 offset:96
	v_add_u32_e32 v84, s85, v122
	v_add_u32_e32 v103, s85, v123
	v_add_u32_e32 v105, s85, v124
	s_waitcnt lgkmcnt(5)
	v_mfma_f32_32x32x16_bf16 v[16:31], v[16:19], v[20:23], 0
	s_waitcnt vmcnt(0)
	v_add_u32_e32 v83, s85, v125
	ds_read_b32 v178, v127 offset:64768
	ds_read_b128 v[180:183], v84 offset:64512
	ds_read_b128 v[184:187], v103 offset:64512
	ds_read_b128 v[188:191], v105 offset:64512
	ds_read_b128 v[196:199], v83 offset:64512
	s_waitcnt lgkmcnt(9)
	v_mfma_f32_32x32x16_bf16 v[16:31], v[34:37], v[38:41], v[16:31]
	s_waitcnt lgkmcnt(7)
	v_mfma_f32_32x32x16_bf16 v[16:31], v[162:165], v[166:169], v[16:31]
	s_waitcnt lgkmcnt(5)
	v_mfma_f32_32x32x16_bf16 v[16:31], v[170:173], v[174:177], v[16:31]
	s_waitcnt lgkmcnt(0)
	v_sub_f32_e32 v35, v180, v178
	v_sub_f32_e32 v36, v181, v178
	v_min_f32_e32 v36, 0, v36
	v_mul_f32_e32 v36, 0x3fb8aa3b, v36
	v_exp_f32_e32 v36, v36
	v_min_f32_e32 v35, 0, v35
	v_mul_f32_e32 v35, 0x3fb8aa3b, v35
	v_exp_f32_e32 v35, v35
	s_nop 0
	v_mul_f32_e32 v17, v17, v36
	v_sub_f32_e32 v36, v182, v178
	v_min_f32_e32 v36, 0, v36
	v_mul_f32_e32 v36, 0x3fb8aa3b, v36
	v_exp_f32_e32 v36, v36
	v_mul_f32_e32 v16, v16, v35
	v_cndmask_b32_e64 v16, 0, v16, s[8:9]
	v_add_f32_e32 v35, 0, v16
	v_mul_f32_e32 v18, v18, v36
	v_sub_f32_e32 v36, v183, v178
	v_min_f32_e32 v36, 0, v36
	v_mul_f32_e32 v36, 0x3fb8aa3b, v36
	v_exp_f32_e32 v36, v36
	v_cndmask_b32_e64 v17, 0, v17, s[10:11]
	v_cndmask_b32_e64 v18, 0, v18, s[12:13]
	v_add_f32_e32 v35, v17, v35
	v_mul_f32_e32 v19, v19, v36
	v_cndmask_b32_e64 v19, 0, v19, s[14:15]
	v_cvt_pk_bf16_f32 v16, v16, v17
	v_cvt_pk_bf16_f32 v17, v18, v19
	v_add_f32_e32 v35, v18, v35
	ds_write_b64 v128, v[16:17] offset:36864
	v_add_f32_e32 v35, v19, v35
	v_sub_f32_e32 v16, v184, v178
	v_min_f32_e32 v16, 0, v16
	v_sub_f32_e32 v17, v185, v178
	v_sub_f32_e32 v18, v186, v178
	v_sub_f32_e32 v19, v187, v178
	v_mul_f32_e32 v16, 0x3fb8aa3b, v16
	v_min_f32_e32 v17, 0, v17
	v_min_f32_e32 v18, 0, v18
	v_min_f32_e32 v19, 0, v19
	v_exp_f32_e32 v16, v16
	v_mul_f32_e32 v17, 0x3fb8aa3b, v17
	v_mul_f32_e32 v18, 0x3fb8aa3b, v18
	v_mul_f32_e32 v19, 0x3fb8aa3b, v19
	v_exp_f32_e32 v17, v17
	v_exp_f32_e32 v18, v18
	v_exp_f32_e32 v19, v19
	v_mul_f32_e32 v16, v20, v16
	v_cndmask_b32_e64 v16, 0, v16, s[16:17]
	v_mul_f32_e32 v17, v21, v17
	v_mul_f32_e32 v18, v22, v18
	v_mul_f32_e32 v19, v23, v19
	v_add_f32_e32 v20, v16, v35
	v_cndmask_b32_e64 v17, 0, v17, s[18:19]
	v_cndmask_b32_e64 v18, 0, v18, s[20:21]
	v_cndmask_b32_e64 v19, 0, v19, s[22:23]
	v_add_f32_e32 v20, v17, v20
	v_cvt_pk_bf16_f32 v16, v16, v17
	v_cvt_pk_bf16_f32 v17, v18, v19
	v_add_f32_e32 v20, v18, v20
	ds_write_b64 v129, v[16:17] offset:36864
	v_add_f32_e32 v20, v19, v20
	v_sub_f32_e32 v16, v188, v178
	v_min_f32_e32 v16, 0, v16
	v_sub_f32_e32 v17, v189, v178
	v_sub_f32_e32 v18, v190, v178
	v_sub_f32_e32 v19, v191, v178
	v_mul_f32_e32 v16, 0x3fb8aa3b, v16
	v_min_f32_e32 v17, 0, v17
	v_min_f32_e32 v18, 0, v18
	v_min_f32_e32 v19, 0, v19
	v_exp_f32_e32 v16, v16
	v_mul_f32_e32 v17, 0x3fb8aa3b, v17
	v_mul_f32_e32 v18, 0x3fb8aa3b, v18
	v_mul_f32_e32 v19, 0x3fb8aa3b, v19
	v_exp_f32_e32 v17, v17
	v_exp_f32_e32 v18, v18
	v_exp_f32_e32 v19, v19
	v_mul_f32_e32 v16, v24, v16
	v_cndmask_b32_e64 v16, 0, v16, s[24:25]
	v_mul_f32_e32 v17, v25, v17
	v_mul_f32_e32 v18, v26, v18
	v_mul_f32_e32 v19, v27, v19
	v_add_f32_e32 v20, v16, v20
	v_cndmask_b32_e64 v17, 0, v17, s[26:27]
	v_cndmask_b32_e64 v18, 0, v18, s[28:29]
	v_cndmask_b32_e64 v19, 0, v19, s[30:31]
	v_add_f32_e32 v20, v17, v20
	v_cvt_pk_bf16_f32 v16, v16, v17
	v_cvt_pk_bf16_f32 v17, v18, v19
	v_add_f32_e32 v20, v18, v20
	ds_write_b64 v131, v[16:17] offset:36864
	v_add_f32_e32 v20, v19, v20
	v_sub_f32_e32 v16, v196, v178
	v_min_f32_e32 v16, 0, v16
	v_sub_f32_e32 v18, v198, v178
	v_mul_f32_e32 v16, 0x3fb8aa3b, v16
	v_min_f32_e32 v18, 0, v18
	v_exp_f32_e32 v16, v16
	v_mul_f32_e32 v18, 0x3fb8aa3b, v18
	v_exp_f32_e32 v18, v18
	v_sub_f32_e32 v17, v197, v178
	v_mul_f32_e32 v16, v28, v16
	v_cndmask_b32_e64 v21, 0, v16, s[34:35]
	v_min_f32_e32 v17, 0, v17
	v_mul_f32_e32 v18, v30, v18
	v_add_f32_e32 v16, v21, v20
	v_mul_f32_e32 v17, 0x3fb8aa3b, v17
	v_cndmask_b32_e64 v20, 0, v18, s[38:39]
	v_sub_f32_e32 v18, v199, v178
	v_exp_f32_e32 v17, v17
	v_min_f32_e32 v18, 0, v18
	v_mul_f32_e32 v18, 0x3fb8aa3b, v18
	v_exp_f32_e32 v18, v18
	v_mul_f32_e32 v17, v29, v17
	v_cndmask_b32_e64 v17, 0, v17, s[36:37]
	v_add_f32_e32 v16, v17, v16
	v_mul_f32_e32 v18, v31, v18
	v_add_f32_e32 v16, v20, v16
	v_cndmask_b32_e64 v19, 0, v18, s[40:41]
	v_add_f32_e32 v16, v19, v16
	v_cvt_pk_bf16_f32 v18, v21, v17
	ds_bpermute_b32 v17, v117, v16
	v_cvt_pk_bf16_f32 v19, v20, v19
	ds_write_b64 v132, v[18:19] offset:36864
	s_and_saveexec_b64 s[76:77], s[6:7]
	s_cbranch_execz .LBB0_466
	s_waitcnt lgkmcnt(1)
	v_add_f32_e32 v16, v16, v17
	ds_write_b32 v133, v16 offset:64512
